# P7 last round: each unit shared by WG pair (row halves), other-half MFMAs skipped
# speedup vs baseline: 1.0063x; 1.0063x over previous
;     __host__ __device__ bool next(int i, Unit& u) const {
;         const long L = (long)i * G + c; if (L >= nwg) return false;
;         int wgid = (int)L; { const int q = nwg / NXCD, r = nwg % NXCD, xcd = wgid % NXCD, off = wgid / NXCD; wgid = (xcd < r ? xcd * (q + 1) : r * (q + 1) + (xcd - r) * q) + off; }
;         const int nig = WGM * nN, gid = wgid / nig, fm = gid * WGM, gsz = (nM - fm) < WGM ? (nM - fm) : WGM;
;         u.pm = fm + ((wgid % nig) % gsz); u.pn = (wgid % nig) / gsz; return true;
;     }
; template <class Epi, class Sched, bool ALIGN_EPI = false, bool SP2 = false>
; __device__ __forceinline__ void gemm_phase(PG8_LAS unsigned char* lds, const Gemm g, const Sched& S, const Epi& E) {
;     ...
;         const bool has_next = S.next(ui + 1, nxt);
;         const char* nA = has_next ? (const char*)g.A + (size_t)nxt.pm * tstepA : cA; const char* nB = has_next ? (const char*)g.Bt + (size_t)nxt.pn * tstepB : cB;
;         for (int t = 0; t < nt; t += 2) {
;             const bool last = (t == nt - 2);
;             if constexpr (Epi::HAS_MID) { if (t == E.mid_t) E.mid(acc, cur, wr, wc, fr, fq); }
;             const char* a1 = cA + (size_t)(t + 1) * kstep;
;             const char* a2 = last ? nA : cA + (size_t)(t + 2) * kstep; const char* b2 = last ? nB : cB + (size_t)(t + 2) * kstep;
;             const char* a3 = a2 + kstep; const char* b3 = b2 + kstep;
;             if (last && has_next) S.a_ready(nxt);
;             if constexpr (SP2) {
;             PG8_LDB(B0, 0, 0); PG8_LDB(B1, 0, 1); PG8_SCHED; PG8_LDA(At, 0, 0); PG8_STAGE(PG8_SA(1, 1), a1 + hstepA, voffA);
;             PG8_WAIT_V(8); PG8_WAIT_L(0); PG8_BAR; PG8_MMA(0, 0, At, B0); PG8_MMA(0, 1, At, B1); PG8_BAR; PG8_SCHED;
;             PG8_LDA(At, 0, 1); PG8_STAGE(PG8_SB(0, 0), b2, voffB); PG8_STAGE(PG8_SB(0, 1), b2 + hstepB, voffB); PG8_STAGE(PG8_SA(0, 0), a2, voffA);
;             PG8_WAIT_V(8); PG8_WAIT_L(0); PG8_BAR; PG8_MMA(1, 0, At, B0); PG8_MMA(1, 1, At, B1); PG8_BAR; PG8_SCHED;
;             PG8_LDB(B0, 1, 0); PG8_LDB(B1, 1, 1); PG8_SCHED; PG8_LDA(At, 1, 0); PG8_STAGE(PG8_SA(0, 1), a2 + hstepA, voffA);
;             PG8_WAIT_V(8); PG8_WAIT_L(0); PG8_BAR; PG8_MMA(0, 0, At, B0); PG8_MMA(0, 1, At, B1); PG8_BAR; PG8_SCHED;
;             PG8_LDA(At, 1, 1); PG8_STAGE(PG8_SB(1, 0), b3, voffB); PG8_STAGE(PG8_SB(1, 1), b3 + hstepB, voffB); PG8_STAGE(PG8_SA(1, 0), a3, voffA);
.LBB0_1821:
	s_add_i32 s57, s57, 1
	s_mul_i32 s21, s57, s11
	s_mul_hi_u32 s23, s57, s10
	s_add_i32 s23, s23, s21
	s_mul_i32 s21, s57, s10
	s_add_u32 s26, s21, s72
	s_addc_u32 s27, s23, s73
	s_cmp_eq_u32 s57, 5
	s_cbranch_scc0 .Lp7_noadj
	s_cmp_lt_u32 s72, 128
	s_cbranch_scc1 .Lp7_noadj
	s_sub_u32 s26, s26, 128
	s_subb_u32 s27, s27, 0
.Lp7_noadj:
	v_cmp_gt_i64_e32 vcc, s[26:27], v[142:143]
	v_cmp_lt_i64_e64 s[36:37], s[26:27], v[140:141]
	s_cbranch_vccnz .LBB0_1823
	s_ashr_i32 s21, s26, 31
	s_lshr_b32 s21, s21, 29
	s_add_i32 s21, s26, s21
	s_ashr_i32 s22, s21, 3
	s_and_b32 s21, s21, -8
	s_sub_i32 s21, s26, s21
	s_cmp_lt_i32 s21, 0
	s_cselect_b32 s23, s5, 0xb0
	s_mul_i32 s21, s21, s23
	s_add_i32 s21, s21, s22
	s_mul_hi_i32 s22, s21, 0x2e8ba2e9
	s_lshr_b32 s23, s22, 31
	s_ashr_i32 s22, s22, 6
	s_add_i32 s22, s22, s23
	s_lshl_b32 s23, s22, 3
	s_sub_i32 s24, 32, s23
	s_min_i32 s24, s24, 8
	s_abs_i32 s25, s24
	v_cvt_f32_u32_e32 v0, s25
	s_sub_i32 s27, 0, s25
	s_mulk_i32 s22, 0x160
	s_sub_i32 s21, s21, s22
	v_rcp_iflag_f32_e32 v0, v0
	s_abs_i32 s22, s21
	s_xor_b32 s26, s21, s24
	s_ashr_i32 s26, s26, 31
	v_mul_f32_e32 v0, 0x4f7ffffe, v0
	v_cvt_u32_f32_e32 v0, v0
	s_nop 0
	v_readfirstlane_b32 s28, v0
	s_mul_i32 s27, s27, s28
	s_mul_hi_u32 s27, s28, s27
	s_add_i32 s28, s28, s27
	s_mul_hi_u32 s27, s22, s28
	s_mul_i32 s28, s27, s25
	s_sub_i32 s22, s22, s28
	s_add_i32 s29, s27, 1
	s_sub_i32 s28, s22, s25
	s_cmp_ge_u32 s22, s25
	s_cselect_b32 s27, s29, s27
	s_cselect_b32 s22, s28, s22
	s_add_i32 s28, s27, 1
	s_cmp_ge_u32 s22, s25
	s_cselect_b32 s22, s28, s27
	s_xor_b32 s22, s22, s26
	s_sub_i32 s22, s22, s26
	s_mul_i32 s24, s22, s24
	s_sub_i32 s21, s21, s24
	s_add_i32 s24, s23, s21
.LBB0_1823:
	s_ashr_i32 s25, s24, 31
	s_lshl_b64 s[26:27], s[24:25], 20
	s_add_u32 s26, s48, s26
	s_addc_u32 s27, s49, s27
	s_and_b64 s[28:29], s[36:37], exec
	s_cselect_b32 s21, s27, s31
	s_cselect_b32 s25, s26, s30
	s_ashr_i32 s23, s22, 31
	s_lshl_b64 s[28:29], s[22:23], 20
	s_add_u32 s28, s90, s28
	s_addc_u32 s29, s91, s29
	s_and_b64 s[38:39], s[36:37], exec
	s_cselect_b32 s23, s29, s35
	s_cselect_b32 s59, s28, s34
	s_add_u32 s30, s30, 0x80080
	s_addc_u32 s31, s31, 0
	s_add_u32 s60, s34, 0x100
	v_mov_b32_e32 v0, 0
	s_addc_u32 s61, s35, 0
	s_mov_b32 s62, -2
	v_mov_b32_e32 v1, v0
	v_mov_b32_e32 v2, v0
	v_mov_b32_e32 v3, v0
	v_mov_b32_e32 v8, v0
	v_mov_b32_e32 v9, v0
	v_mov_b32_e32 v10, v0
	v_mov_b32_e32 v11, v0
	v_mov_b32_e32 v16, v0
	v_mov_b32_e32 v17, v0
	v_mov_b32_e32 v18, v0
	v_mov_b32_e32 v19, v0
	v_mov_b32_e32 v24, v0
	v_mov_b32_e32 v25, v0
	v_mov_b32_e32 v26, v0
	v_mov_b32_e32 v27, v0
	v_mov_b32_e32 v32, v0
	v_mov_b32_e32 v33, v0
	v_mov_b32_e32 v34, v0
	v_mov_b32_e32 v35, v0
	v_mov_b32_e32 v40, v0
	v_mov_b32_e32 v41, v0
	v_mov_b32_e32 v42, v0
	v_mov_b32_e32 v43, v0
	v_mov_b32_e32 v48, v0
	v_mov_b32_e32 v49, v0
	v_mov_b32_e32 v50, v0
	v_mov_b32_e32 v51, v0
	v_mov_b32_e32 v56, v0
	v_mov_b32_e32 v57, v0
	v_mov_b32_e32 v58, v0
	v_mov_b32_e32 v59, v0
	v_mov_b32_e32 v4, v0
	v_mov_b32_e32 v5, v0
	v_mov_b32_e32 v6, v0
	v_mov_b32_e32 v7, v0
	v_mov_b32_e32 v12, v0
	v_mov_b32_e32 v13, v0
	v_mov_b32_e32 v14, v0
	v_mov_b32_e32 v15, v0
	v_mov_b32_e32 v20, v0
	v_mov_b32_e32 v21, v0
	v_mov_b32_e32 v22, v0
	v_mov_b32_e32 v23, v0
	v_mov_b32_e32 v28, v0
	v_mov_b32_e32 v29, v0
	v_mov_b32_e32 v30, v0
	v_mov_b32_e32 v31, v0
	v_mov_b32_e32 v36, v0
	v_mov_b32_e32 v37, v0
	v_mov_b32_e32 v38, v0
	v_mov_b32_e32 v39, v0
	v_mov_b32_e32 v44, v0
	v_mov_b32_e32 v45, v0
	v_mov_b32_e32 v46, v0
	v_mov_b32_e32 v47, v0
	v_mov_b32_e32 v52, v0
	v_mov_b32_e32 v53, v0
	v_mov_b32_e32 v54, v0
	v_mov_b32_e32 v55, v0
	v_mov_b32_e32 v60, v0
	v_mov_b32_e32 v61, v0
	v_mov_b32_e32 v62, v0
	v_mov_b32_e32 v63, v0
	v_mov_b32_e32 v64, v0
	v_mov_b32_e32 v65, v0
	v_mov_b32_e32 v66, v0
	v_mov_b32_e32 v67, v0
	v_mov_b32_e32 v72, v0
	v_mov_b32_e32 v73, v0
	v_mov_b32_e32 v74, v0
	v_mov_b32_e32 v75, v0
	v_mov_b32_e32 v80, v0
	v_mov_b32_e32 v81, v0
	v_mov_b32_e32 v82, v0
	v_mov_b32_e32 v83, v0
	v_mov_b32_e32 v88, v0
	v_mov_b32_e32 v89, v0
	v_mov_b32_e32 v90, v0
	v_mov_b32_e32 v91, v0
	v_mov_b32_e32 v96, v0
	v_mov_b32_e32 v97, v0
	v_mov_b32_e32 v98, v0
	v_mov_b32_e32 v99, v0
	v_mov_b32_e32 v104, v0
	v_mov_b32_e32 v105, v0
	v_mov_b32_e32 v106, v0
	v_mov_b32_e32 v107, v0
	v_mov_b32_e32 v112, v0
	v_mov_b32_e32 v113, v0
	v_mov_b32_e32 v114, v0
	v_mov_b32_e32 v115, v0
	v_mov_b32_e32 v120, v0
	v_mov_b32_e32 v121, v0
	v_mov_b32_e32 v122, v0
	v_mov_b32_e32 v123, v0
	v_mov_b32_e32 v68, v0
	v_mov_b32_e32 v69, v0
	v_mov_b32_e32 v70, v0
	v_mov_b32_e32 v71, v0
	v_mov_b32_e32 v76, v0
	v_mov_b32_e32 v77, v0
	v_mov_b32_e32 v78, v0
	v_mov_b32_e32 v79, v0
	v_mov_b32_e32 v84, v0
	v_mov_b32_e32 v85, v0
	v_mov_b32_e32 v86, v0
	v_mov_b32_e32 v87, v0
	v_mov_b32_e32 v92, v0
	v_mov_b32_e32 v93, v0
	v_mov_b32_e32 v94, v0
	v_mov_b32_e32 v95, v0
	v_mov_b32_e32 v100, v0
	v_mov_b32_e32 v101, v0
	v_mov_b32_e32 v102, v0
	v_mov_b32_e32 v103, v0
	v_mov_b32_e32 v108, v0
	v_mov_b32_e32 v109, v0
	v_mov_b32_e32 v110, v0
	v_mov_b32_e32 v111, v0
	v_mov_b32_e32 v116, v0
	v_mov_b32_e32 v117, v0
	v_mov_b32_e32 v118, v0
	v_mov_b32_e32 v119, v0
	v_mov_b32_e32 v124, v0
	v_mov_b32_e32 v125, v0
	v_mov_b32_e32 v126, v0
	v_mov_b32_e32 v127, v0
	s_cmp_eq_u32 s57, 6
	s_cbranch_scc1 .Lp7_half_dispatch

; #define PG8_BAR __builtin_amdgcn_s_barrier()
; template <class Epi, class Sched, bool ALIGN_EPI = false, bool SP2 = false>
; __device__ __forceinline__ void gemm_phase(PG8_LAS unsigned char* lds, const Gemm g, const Sched& S, const Epi& E) {
;     ...
;         if constexpr (ALIGN_EPI) { if (wr == 0) PG8_BAR; }
;         if constexpr (!Epi::AFTER_DRAIN) { E(acc, cur, wr, wc, fr, fq); S.done(cur); }
.Lp7_after_loop:
	s_and_b64 vcc, exec, s[18:19]
	s_cbranch_vccz .LBB0_1827
	s_barrier

; __device__ __forceinline__ float sigmoidf_(float x) { return __builtin_amdgcn_rcpf(1.0f + __expf(-x)); }
; __device__ __forceinline__ u32x4 pack8(const f32x4& a, const f32x4& b) { u32x4 w; w.x = cvt_pk_bf16(a[0], a[1]); w.y = cvt_pk_bf16(a[2], a[3]); w.z = cvt_pk_bf16(b[0], b[1]); w.w = cvt_pk_bf16(b[2], b[3]); return w; }
;     __device__ __forceinline__ void operator()(const f32x4 (&acc)[2][2][4][2], const Unit& u, int wr, int wc, int fr, int fq) const {
;     ...
; #pragma unroll
;         for (int ai = 0; ai < 2; ++ai)
; #pragma unroll
;             for (int m = 0; m < 4; ++m) { const size_t row = (size_t)u.pm * BM + ai * HALF + wr * 64 + m * 16 + fr;
;                 const float rs = tab[ai * HALF + wr * 64 + m * 16 + fr];
;                 f32x4 h[2];
; #pragma unroll
;                 for (int n = 0; n < 2; ++n) { const f32x4 g = acc[ai][0][m][n] * rs, up = acc[ai][1][m][n] * rs;
; #pragma unroll
;                     for (int j = 0; j < 4; ++j) h[n][j] = g[j] * sigmoidf_(g[j]) * up[j]; }
;                 *(u32x4*)(H + row * 5632 + u.pn * HALF + wc * 32 + fq * 8) = pack8(h[0], h[1]); }
.LBB0_1833:
	s_ashr_i32 s21, s20, 31
	s_lshl_b64 s[20:21], s[20:21], 8
	s_add_u32 s20, s20, s43
	s_addc_u32 s21, s21, s51
	v_ashrrev_i32_e32 v145, 31, v144
	v_lshl_add_u32 v155, v144, 2, s52
	v_lshl_add_u64 v[146:147], s[20:21], 0, v[144:145]
	v_lshlrev_b32_e32 v144, 3, v156
	s_cmp_eq_u32 s57, 6
	s_cbranch_scc0 .Lp7_epi_full
	s_cmp_ge_u32 s72, 128
	s_cbranch_scc1 .Lp7_h1_epi
.Lp7_epi_full:
	ds_read_b32 v156, v155
	v_mov_b32_e32 v158, v120
	v_mov_b32_e32 v159, v124
	v_mov_b32_e32 v124, v121
	s_lshl_b32 s20, s58, 7
	s_waitcnt lgkmcnt(0)
	v_pk_mul_f32 v[158:159], v[158:159], v[156:157] op_sel_hi:[1,0]
	s_ashr_i32 s21, s20, 31
	v_mul_f32_e32 v120, 0xbfb8aa3b, v159
	v_exp_f32_e32 v120, v120
	v_ashrrev_i32_e32 v145, 31, v144
	v_add_f32_e32 v120, 1.0, v120
	v_rcp_f32_e32 v120, v120
	s_nop 0
	v_mul_f32_e32 v120, v159, v120
	v_mul_f32_e32 v157, v158, v120
	v_pk_mul_f32 v[120:121], v[124:125], v[156:157] op_sel_hi:[1,0]
	s_nop 0
	v_mul_f32_e32 v124, 0xbfb8aa3b, v121
	v_exp_f32_e32 v124, v124
	s_nop 0
	v_add_f32_e32 v124, 1.0, v124
	v_rcp_f32_e32 v124, v124
	s_nop 0
	v_mul_f32_e32 v121, v121, v124
	v_mul_f32_e32 v124, v120, v121
	v_mov_b32_e32 v120, v122
	v_mov_b32_e32 v121, v126
	v_pk_mul_f32 v[120:121], v[120:121], v[156:157] op_sel_hi:[1,0]
	v_mov_b32_e32 v126, v123
	v_mul_f32_e32 v122, 0xbfb8aa3b, v121
	v_exp_f32_e32 v122, v122
	s_nop 0
	v_add_f32_e32 v122, 1.0, v122
	v_rcp_f32_e32 v122, v122
	s_nop 0
	v_mul_f32_e32 v121, v121, v122
	v_mul_f32_e32 v122, v120, v121
	v_pk_mul_f32 v[120:121], v[126:127], v[156:157] op_sel_hi:[1,0]
	s_nop 0
	v_mul_f32_e32 v123, 0xbfb8aa3b, v121
	v_exp_f32_e32 v123, v123
	s_nop 0
	v_add_f32_e32 v123, 1.0, v123
	v_rcp_f32_e32 v123, v123
	s_nop 0
	v_mul_f32_e32 v121, v121, v123
	v_mul_f32_e32 v123, v120, v121
	v_mov_b32_e32 v120, v112
	v_mov_b32_e32 v121, v116
	v_pk_mul_f32 v[120:121], v[120:121], v[156:157] op_sel_hi:[1,0]
	v_mov_b32_e32 v116, v113
	v_mul_f32_e32 v112, 0xbfb8aa3b, v121
	v_exp_f32_e32 v112, v112
	s_nop 0
	v_add_f32_e32 v112, 1.0, v112
	v_rcp_f32_e32 v112, v112
	s_nop 0
	v_mul_f32_e32 v112, v121, v112
	v_mul_f32_e32 v120, v120, v112
	v_pk_mul_f32 v[112:113], v[116:117], v[156:157] op_sel_hi:[1,0]
	s_nop 0
	v_mul_f32_e32 v116, 0xbfb8aa3b, v113
	v_exp_f32_e32 v116, v116
	s_nop 0
	v_add_f32_e32 v116, 1.0, v116
	v_rcp_f32_e32 v116, v116
	s_nop 0
	v_mul_f32_e32 v113, v113, v116
	v_mul_f32_e32 v116, v112, v113
	v_mov_b32_e32 v112, v114
	v_mov_b32_e32 v113, v118
	v_pk_mul_f32 v[112:113], v[112:113], v[156:157] op_sel_hi:[1,0]
	v_mov_b32_e32 v118, v115
	v_mul_f32_e32 v114, 0xbfb8aa3b, v113
	v_exp_f32_e32 v114, v114
	s_nop 0
	v_add_f32_e32 v114, 1.0, v114
	v_rcp_f32_e32 v114, v114
	s_nop 0
	v_mul_f32_e32 v113, v113, v114
	v_mul_f32_e32 v117, v112, v113
	v_pk_mul_f32 v[112:113], v[118:119], v[156:157] op_sel_hi:[1,0]
	s_nop 0
	v_mul_f32_e32 v114, 0xbfb8aa3b, v113
	v_exp_f32_e32 v114, v114
	s_nop 0
	v_add_f32_e32 v114, 1.0, v114
	v_rcp_f32_e32 v114, v114
	s_nop 0
	v_mul_f32_e32 v113, v113, v114
	v_mul_f32_e32 v112, v112, v113
	v_cvt_pk_bf16_f32 v114, v157, v124
	v_cvt_pk_bf16_f32 v115, v122, v123
	v_cvt_pk_bf16_f32 v116, v120, v116
	v_cvt_pk_bf16_f32 v117, v117, v112
	v_mov_b64_e32 v[112:113], s[44:45]
	v_mad_u64_u32 v[112:113], s[30:31], v146, s56, v[112:113]
	v_mad_i32_i24 v113, v147, s56, v113
	v_lshl_add_u64 v[112:113], s[20:21], 1, v[112:113]
	v_lshl_add_u64 v[112:113], v[112:113], 0, s[12:13]
	v_lshl_add_u64 v[112:113], v[144:145], 1, v[112:113]
	global_store_dwordx4 v[112:113], v[114:117], off
	ds_read_b32 v114, v155 offset:64
	s_mov_b32 s20, 0x2c000
	v_mov_b32_e32 v116, v104
	v_mov_b32_e32 v117, v108
	v_mov_b32_e32 v108, v105
	s_waitcnt lgkmcnt(0)
	v_pk_mul_f32 v[116:117], v[116:117], v[114:115] op_sel_hi:[1,0]
	s_nop 0
	v_mul_f32_e32 v104, 0xbfb8aa3b, v117
	v_exp_f32_e32 v104, v104
	s_nop 0
	v_add_f32_e32 v104, 1.0, v104
	v_rcp_f32_e32 v104, v104
	s_nop 0
	v_mul_f32_e32 v104, v117, v104
	v_mul_f32_e32 v115, v116, v104
	v_pk_mul_f32 v[104:105], v[108:109], v[114:115] op_sel_hi:[1,0]
	s_nop 0
	v_mul_f32_e32 v108, 0xbfb8aa3b, v105
	v_exp_f32_e32 v108, v108
	s_nop 0
	v_add_f32_e32 v108, 1.0, v108
	v_rcp_f32_e32 v108, v108
	s_nop 0
	v_mul_f32_e32 v105, v105, v108
	v_mul_f32_e32 v108, v104, v105
	v_mov_b32_e32 v104, v106
	v_mov_b32_e32 v105, v110
	v_pk_mul_f32 v[104:105], v[104:105], v[114:115] op_sel_hi:[1,0]
	v_mov_b32_e32 v110, v107
	v_mul_f32_e32 v106, 0xbfb8aa3b, v105
	v_exp_f32_e32 v106, v106
	s_nop 0
	v_add_f32_e32 v106, 1.0, v106
	v_rcp_f32_e32 v106, v106
	s_nop 0
	v_mul_f32_e32 v105, v105, v106
	v_mul_f32_e32 v106, v104, v105
	v_pk_mul_f32 v[104:105], v[110:111], v[114:115] op_sel_hi:[1,0]
	s_nop 0
	v_mul_f32_e32 v107, 0xbfb8aa3b, v105
	v_exp_f32_e32 v107, v107
	s_nop 0
	v_add_f32_e32 v107, 1.0, v107
	v_rcp_f32_e32 v107, v107
	s_nop 0
	v_mul_f32_e32 v105, v105, v107
	v_mul_f32_e32 v107, v104, v105
	v_mov_b32_e32 v104, v96
	v_mov_b32_e32 v105, v100
	v_pk_mul_f32 v[104:105], v[104:105], v[114:115] op_sel_hi:[1,0]
	v_mov_b32_e32 v100, v97
	v_mul_f32_e32 v96, 0xbfb8aa3b, v105
	v_exp_f32_e32 v96, v96
	s_nop 0
	v_add_f32_e32 v96, 1.0, v96
	v_rcp_f32_e32 v96, v96
	s_nop 0
	v_mul_f32_e32 v96, v105, v96
	v_mul_f32_e32 v104, v104, v96
	v_pk_mul_f32 v[96:97], v[100:101], v[114:115] op_sel_hi:[1,0]
	s_nop 0
	v_mul_f32_e32 v100, 0xbfb8aa3b, v97
	v_exp_f32_e32 v100, v100
	s_nop 0
	v_add_f32_e32 v100, 1.0, v100
	v_rcp_f32_e32 v100, v100
	s_nop 0
	v_mul_f32_e32 v97, v97, v100
	v_mul_f32_e32 v100, v96, v97
	v_mov_b32_e32 v96, v98
	v_mov_b32_e32 v97, v102
	v_pk_mul_f32 v[96:97], v[96:97], v[114:115] op_sel_hi:[1,0]
	v_mov_b32_e32 v102, v99
	v_mul_f32_e32 v98, 0xbfb8aa3b, v97
	v_exp_f32_e32 v98, v98
	s_nop 0
	v_add_f32_e32 v98, 1.0, v98
	v_rcp_f32_e32 v98, v98
	s_nop 0
	v_mul_f32_e32 v97, v97, v98
	v_mul_f32_e32 v101, v96, v97
	v_pk_mul_f32 v[96:97], v[102:103], v[114:115] op_sel_hi:[1,0]
	s_nop 0
	v_mul_f32_e32 v98, 0xbfb8aa3b, v97
	v_exp_f32_e32 v98, v98
	s_nop 0
	v_add_f32_e32 v98, 1.0, v98
	v_rcp_f32_e32 v98, v98
	s_nop 0
	v_mul_f32_e32 v97, v97, v98
	v_mul_f32_e32 v99, v96, v97
	v_cvt_pk_bf16_f32 v96, v115, v108
	v_cvt_pk_bf16_f32 v97, v106, v107
	v_cvt_pk_bf16_f32 v98, v104, v100
	v_add_co_u32_e32 v100, vcc, s20, v112
	v_cvt_pk_bf16_f32 v99, v101, v99
	s_mov_b32 s20, 0x58000
	s_nop 0
	v_addc_co_u32_e32 v101, vcc, 0, v113, vcc
	global_store_dwordx4 v[100:101], v[96:99], off
	ds_read_b32 v96, v155 offset:128
	s_nop 0
	v_mov_b32_e32 v98, v88
	v_mov_b32_e32 v99, v92
	v_mov_b32_e32 v92, v89
	s_waitcnt lgkmcnt(0)
; __device__ __forceinline__ float sigmoidf_(float x) { return __builtin_amdgcn_rcpf(1.0f + __expf(-x)); }
; __device__ __forceinline__ u32x4 pack8(const f32x4& a, const f32x4& b) { u32x4 w; w.x = cvt_pk_bf16(a[0], a[1]); w.y = cvt_pk_bf16(a[2], a[3]); w.z = cvt_pk_bf16(b[0], b[1]); w.w = cvt_pk_bf16(b[2], b[3]); return w; }
;     __device__ __forceinline__ void operator()(const f32x4 (&acc)[2][2][4][2], const Unit& u, int wr, int wc, int fr, int fq) const {
;     ...
; #pragma unroll
;         for (int ai = 0; ai < 2; ++ai)
; #pragma unroll
;             for (int m = 0; m < 4; ++m) { const size_t row = (size_t)u.pm * BM + ai * HALF + wr * 64 + m * 16 + fr;
;                 const float rs = tab[ai * HALF + wr * 64 + m * 16 + fr];
;                 f32x4 h[2];
; #pragma unroll
;                 for (int n = 0; n < 2; ++n) { const f32x4 g = acc[ai][0][m][n] * rs, up = acc[ai][1][m][n] * rs;
; #pragma unroll
;                     for (int j = 0; j < 4; ++j) h[n][j] = g[j] * sigmoidf_(g[j]) * up[j]; }
;                 *(u32x4*)(H + row * 5632 + u.pn * HALF + wc * 32 + fq * 8) = pack8(h[0], h[1]); }
	v_pk_mul_f32 v[98:99], v[98:99], v[96:97] op_sel_hi:[1,0]
	s_nop 0
	v_mul_f32_e32 v88, 0xbfb8aa3b, v99
	v_exp_f32_e32 v88, v88
	s_nop 0
	v_add_f32_e32 v88, 1.0, v88
	v_rcp_f32_e32 v88, v88
	s_nop 0
	v_mul_f32_e32 v88, v99, v88
	v_mul_f32_e32 v97, v98, v88
	v_pk_mul_f32 v[88:89], v[92:93], v[96:97] op_sel_hi:[1,0]
	s_nop 0
	v_mul_f32_e32 v92, 0xbfb8aa3b, v89
	v_exp_f32_e32 v92, v92
	s_nop 0
	v_add_f32_e32 v92, 1.0, v92
	v_rcp_f32_e32 v92, v92
	s_nop 0
	v_mul_f32_e32 v89, v89, v92
	v_mul_f32_e32 v92, v88, v89
	v_mov_b32_e32 v88, v90
	v_mov_b32_e32 v89, v94
	v_pk_mul_f32 v[88:89], v[88:89], v[96:97] op_sel_hi:[1,0]
	v_mov_b32_e32 v94, v91
	v_mul_f32_e32 v90, 0xbfb8aa3b, v89
	v_exp_f32_e32 v90, v90
	s_nop 0
	v_add_f32_e32 v90, 1.0, v90
	v_rcp_f32_e32 v90, v90
	s_nop 0
	v_mul_f32_e32 v89, v89, v90
	v_mul_f32_e32 v90, v88, v89
	v_pk_mul_f32 v[88:89], v[94:95], v[96:97] op_sel_hi:[1,0]
	s_nop 0
	v_mul_f32_e32 v91, 0xbfb8aa3b, v89
	v_exp_f32_e32 v91, v91
	s_nop 0
	v_add_f32_e32 v91, 1.0, v91
	v_rcp_f32_e32 v91, v91
	s_nop 0
	v_mul_f32_e32 v89, v89, v91
	v_mul_f32_e32 v91, v88, v89
	v_mov_b32_e32 v88, v80
	v_mov_b32_e32 v89, v84
	v_pk_mul_f32 v[88:89], v[88:89], v[96:97] op_sel_hi:[1,0]
	v_mov_b32_e32 v84, v81
	v_mul_f32_e32 v80, 0xbfb8aa3b, v89
	v_exp_f32_e32 v80, v80
	s_nop 0
	v_add_f32_e32 v80, 1.0, v80
	v_rcp_f32_e32 v80, v80
	s_nop 0
	v_mul_f32_e32 v80, v89, v80
	v_mul_f32_e32 v88, v88, v80
	v_pk_mul_f32 v[80:81], v[84:85], v[96:97] op_sel_hi:[1,0]
	s_nop 0
	v_mul_f32_e32 v84, 0xbfb8aa3b, v81
	v_exp_f32_e32 v84, v84
	s_nop 0
	v_add_f32_e32 v84, 1.0, v84
	v_rcp_f32_e32 v84, v84
	s_nop 0
	v_mul_f32_e32 v81, v81, v84
	v_mul_f32_e32 v84, v80, v81
	v_mov_b32_e32 v80, v82
	v_mov_b32_e32 v81, v86
	v_pk_mul_f32 v[80:81], v[80:81], v[96:97] op_sel_hi:[1,0]
	v_mov_b32_e32 v86, v83
	v_mul_f32_e32 v82, 0xbfb8aa3b, v81
	v_exp_f32_e32 v82, v82
	s_nop 0
	v_add_f32_e32 v82, 1.0, v82
	v_rcp_f32_e32 v82, v82
	s_nop 0
	v_mul_f32_e32 v81, v81, v82
	v_mul_f32_e32 v85, v80, v81
	v_pk_mul_f32 v[80:81], v[86:87], v[96:97] op_sel_hi:[1,0]
	s_nop 0
	v_mul_f32_e32 v82, 0xbfb8aa3b, v81
	v_exp_f32_e32 v82, v82
	s_nop 0
	v_add_f32_e32 v82, 1.0, v82
	v_rcp_f32_e32 v82, v82
	s_nop 0
	v_mul_f32_e32 v81, v81, v82
	v_mul_f32_e32 v83, v80, v81
	v_cvt_pk_bf16_f32 v80, v97, v92
	v_cvt_pk_bf16_f32 v81, v90, v91
	v_cvt_pk_bf16_f32 v82, v88, v84
	v_add_co_u32_e32 v84, vcc, s20, v112
	v_cvt_pk_bf16_f32 v83, v85, v83
	s_mov_b32 s20, 0x84000
	s_nop 0
	v_addc_co_u32_e32 v85, vcc, 0, v113, vcc
	global_store_dwordx4 v[84:85], v[80:83], off
	ds_read_b32 v80, v155 offset:192
	s_nop 0
	v_mov_b32_e32 v82, v72
	v_mov_b32_e32 v83, v76
	v_mov_b32_e32 v76, v73
	s_waitcnt lgkmcnt(0)
	v_pk_mul_f32 v[82:83], v[82:83], v[80:81] op_sel_hi:[1,0]
	s_nop 0
	v_mul_f32_e32 v72, 0xbfb8aa3b, v83
	v_exp_f32_e32 v72, v72
	s_nop 0
	v_add_f32_e32 v72, 1.0, v72
	v_rcp_f32_e32 v72, v72
	s_nop 0
	v_mul_f32_e32 v72, v83, v72
	v_mul_f32_e32 v81, v82, v72
	v_pk_mul_f32 v[72:73], v[76:77], v[80:81] op_sel_hi:[1,0]
	s_nop 0
	v_mul_f32_e32 v76, 0xbfb8aa3b, v73
	v_exp_f32_e32 v76, v76
	s_nop 0
	v_add_f32_e32 v76, 1.0, v76
	v_rcp_f32_e32 v76, v76
	s_nop 0
	v_mul_f32_e32 v73, v73, v76
	v_mul_f32_e32 v76, v72, v73
	v_mov_b32_e32 v72, v74
	v_mov_b32_e32 v73, v78
	v_pk_mul_f32 v[72:73], v[72:73], v[80:81] op_sel_hi:[1,0]
	v_mov_b32_e32 v78, v75
	v_mul_f32_e32 v74, 0xbfb8aa3b, v73
	v_exp_f32_e32 v74, v74
	s_nop 0
	v_add_f32_e32 v74, 1.0, v74
	v_rcp_f32_e32 v74, v74
	s_nop 0
	v_mul_f32_e32 v73, v73, v74
	v_mul_f32_e32 v74, v72, v73
	v_pk_mul_f32 v[72:73], v[78:79], v[80:81] op_sel_hi:[1,0]
	s_nop 0
	v_mul_f32_e32 v75, 0xbfb8aa3b, v73
	v_exp_f32_e32 v75, v75
	s_nop 0
	v_add_f32_e32 v75, 1.0, v75
	v_rcp_f32_e32 v75, v75
	s_nop 0
	v_mul_f32_e32 v73, v73, v75
	v_mul_f32_e32 v75, v72, v73
	v_mov_b32_e32 v72, v64
	v_mov_b32_e32 v73, v68
	v_pk_mul_f32 v[72:73], v[72:73], v[80:81] op_sel_hi:[1,0]
	v_mov_b32_e32 v68, v65
	v_mul_f32_e32 v64, 0xbfb8aa3b, v73
	v_exp_f32_e32 v64, v64
	s_nop 0
	v_add_f32_e32 v64, 1.0, v64
	v_rcp_f32_e32 v64, v64
	s_nop 0
	v_mul_f32_e32 v64, v73, v64
	v_mul_f32_e32 v72, v72, v64
	v_pk_mul_f32 v[64:65], v[68:69], v[80:81] op_sel_hi:[1,0]
	s_nop 0
	v_mul_f32_e32 v68, 0xbfb8aa3b, v65
	v_exp_f32_e32 v68, v68
	s_nop 0
	v_add_f32_e32 v68, 1.0, v68
	v_rcp_f32_e32 v68, v68
	s_nop 0
	v_mul_f32_e32 v65, v65, v68
	v_mul_f32_e32 v68, v64, v65
	v_mov_b32_e32 v64, v66
	v_mov_b32_e32 v65, v70
	v_pk_mul_f32 v[64:65], v[64:65], v[80:81] op_sel_hi:[1,0]
	v_mov_b32_e32 v70, v67
	v_mul_f32_e32 v66, 0xbfb8aa3b, v65
	v_exp_f32_e32 v66, v66
	s_nop 0
	v_add_f32_e32 v66, 1.0, v66
	v_rcp_f32_e32 v66, v66
	s_nop 0
	v_mul_f32_e32 v65, v65, v66
	v_mul_f32_e32 v69, v64, v65
	v_pk_mul_f32 v[64:65], v[70:71], v[80:81] op_sel_hi:[1,0]
	s_nop 0
	v_mul_f32_e32 v66, 0xbfb8aa3b, v65
	v_exp_f32_e32 v66, v66
	s_nop 0
	v_add_f32_e32 v66, 1.0, v66
	v_rcp_f32_e32 v66, v66
	s_nop 0
	v_mul_f32_e32 v65, v65, v66
	v_mul_f32_e32 v67, v64, v65
	v_cvt_pk_bf16_f32 v64, v81, v76
	v_cvt_pk_bf16_f32 v65, v74, v75
	v_cvt_pk_bf16_f32 v66, v72, v68
	v_add_co_u32_e32 v68, vcc, s20, v112
	v_cvt_pk_bf16_f32 v67, v69, v67
	s_mov_b32 s20, 0x160000
	s_nop 0
	v_addc_co_u32_e32 v69, vcc, 0, v113, vcc
	global_store_dwordx4 v[68:69], v[64:67], off
	s_cmp_eq_u32 s57, 6
	s_cbranch_scc1 .Lp7_h0_skip
; __device__ __forceinline__ float sigmoidf_(float x) { return __builtin_amdgcn_rcpf(1.0f + __expf(-x)); }
; __device__ __forceinline__ u32x4 pack8(const f32x4& a, const f32x4& b) { u32x4 w; w.x = cvt_pk_bf16(a[0], a[1]); w.y = cvt_pk_bf16(a[2], a[3]); w.z = cvt_pk_bf16(b[0], b[1]); w.w = cvt_pk_bf16(b[2], b[3]); return w; }
;     __device__ __forceinline__ void operator()(const f32x4 (&acc)[2][2][4][2], const Unit& u, int wr, int wc, int fr, int fq) const {
;     ...
; #pragma unroll
;         for (int ai = 0; ai < 2; ++ai)
; #pragma unroll
;             for (int m = 0; m < 4; ++m) { const size_t row = (size_t)u.pm * BM + ai * HALF + wr * 64 + m * 16 + fr;
;                 const float rs = tab[ai * HALF + wr * 64 + m * 16 + fr];
;                 f32x4 h[2];
; #pragma unroll
;                 for (int n = 0; n < 2; ++n) { const f32x4 g = acc[ai][0][m][n] * rs, up = acc[ai][1][m][n] * rs;
; #pragma unroll
;                     for (int j = 0; j < 4; ++j) h[n][j] = g[j] * sigmoidf_(g[j]) * up[j]; }
;                 *(u32x4*)(H + row * 5632 + u.pn * HALF + wc * 32 + fq * 8) = pack8(h[0], h[1]); }
.Lp7_blk4:
	ds_read_b32 v64, v155 offset:512
	s_nop 0
	v_mov_b32_e32 v66, v56
	v_mov_b32_e32 v67, v60
	v_mov_b32_e32 v60, v57
	s_waitcnt lgkmcnt(0)
	v_pk_mul_f32 v[66:67], v[66:67], v[64:65] op_sel_hi:[1,0]
	s_nop 0
	v_mul_f32_e32 v56, 0xbfb8aa3b, v67
	v_exp_f32_e32 v56, v56
	s_nop 0
	v_add_f32_e32 v56, 1.0, v56
	v_rcp_f32_e32 v56, v56
	s_nop 0
	v_mul_f32_e32 v56, v67, v56
	v_mul_f32_e32 v65, v66, v56
	v_pk_mul_f32 v[56:57], v[60:61], v[64:65] op_sel_hi:[1,0]
	s_nop 0
	v_mul_f32_e32 v60, 0xbfb8aa3b, v57
	v_exp_f32_e32 v60, v60
	s_nop 0
	v_add_f32_e32 v60, 1.0, v60
	v_rcp_f32_e32 v60, v60
	s_nop 0
	v_mul_f32_e32 v57, v57, v60
	v_mul_f32_e32 v60, v56, v57
	v_mov_b32_e32 v56, v58
	v_mov_b32_e32 v57, v62
	v_pk_mul_f32 v[56:57], v[56:57], v[64:65] op_sel_hi:[1,0]
	v_mov_b32_e32 v62, v59
	v_mul_f32_e32 v58, 0xbfb8aa3b, v57
	v_exp_f32_e32 v58, v58
	s_nop 0
	v_add_f32_e32 v58, 1.0, v58
	v_rcp_f32_e32 v58, v58
	s_nop 0
	v_mul_f32_e32 v57, v57, v58
	v_mul_f32_e32 v58, v56, v57
	v_pk_mul_f32 v[56:57], v[62:63], v[64:65] op_sel_hi:[1,0]
	s_nop 0
	v_mul_f32_e32 v59, 0xbfb8aa3b, v57
	v_exp_f32_e32 v59, v59
	s_nop 0
	v_add_f32_e32 v59, 1.0, v59
	v_rcp_f32_e32 v59, v59
	s_nop 0
	v_mul_f32_e32 v57, v57, v59
	v_mul_f32_e32 v59, v56, v57
	v_mov_b32_e32 v56, v48
	v_mov_b32_e32 v57, v52
	v_pk_mul_f32 v[56:57], v[56:57], v[64:65] op_sel_hi:[1,0]
	v_mov_b32_e32 v52, v49
	v_mul_f32_e32 v48, 0xbfb8aa3b, v57
	v_exp_f32_e32 v48, v48
	s_nop 0
	v_add_f32_e32 v48, 1.0, v48
	v_rcp_f32_e32 v48, v48
	s_nop 0
	v_mul_f32_e32 v48, v57, v48
	v_mul_f32_e32 v56, v56, v48
	v_pk_mul_f32 v[48:49], v[52:53], v[64:65] op_sel_hi:[1,0]
	s_nop 0
	v_mul_f32_e32 v52, 0xbfb8aa3b, v49
	v_exp_f32_e32 v52, v52
	s_nop 0
	v_add_f32_e32 v52, 1.0, v52
	v_rcp_f32_e32 v52, v52
	s_nop 0
	v_mul_f32_e32 v49, v49, v52
	v_mul_f32_e32 v52, v48, v49
	v_mov_b32_e32 v48, v50
	v_mov_b32_e32 v49, v54
	v_pk_mul_f32 v[48:49], v[48:49], v[64:65] op_sel_hi:[1,0]
	v_mov_b32_e32 v54, v51
	v_mul_f32_e32 v50, 0xbfb8aa3b, v49
	v_exp_f32_e32 v50, v50
	s_nop 0
	v_add_f32_e32 v50, 1.0, v50
	v_rcp_f32_e32 v50, v50
	s_nop 0
	v_mul_f32_e32 v49, v49, v50
	v_mul_f32_e32 v53, v48, v49
	v_pk_mul_f32 v[48:49], v[54:55], v[64:65] op_sel_hi:[1,0]
	s_nop 0
	v_mul_f32_e32 v50, 0xbfb8aa3b, v49
	v_exp_f32_e32 v50, v50
	s_nop 0
	v_add_f32_e32 v50, 1.0, v50
	v_rcp_f32_e32 v50, v50
	s_nop 0
	v_mul_f32_e32 v49, v49, v50
	v_mul_f32_e32 v51, v48, v49
	v_cvt_pk_bf16_f32 v48, v65, v60
	v_cvt_pk_bf16_f32 v49, v58, v59
	v_cvt_pk_bf16_f32 v50, v56, v52
	v_add_co_u32_e32 v52, vcc, s20, v112
	v_cvt_pk_bf16_f32 v51, v53, v51
	s_mov_b32 s20, 0x18c000
	s_nop 0
	v_addc_co_u32_e32 v53, vcc, 0, v113, vcc
	global_store_dwordx4 v[52:53], v[48:51], off
	ds_read_b32 v48, v155 offset:576
	s_nop 0
	v_mov_b32_e32 v50, v40
	v_mov_b32_e32 v51, v44
	v_mov_b32_e32 v44, v41
	s_waitcnt lgkmcnt(0)
	v_pk_mul_f32 v[50:51], v[50:51], v[48:49] op_sel_hi:[1,0]
	s_nop 0
	v_mul_f32_e32 v40, 0xbfb8aa3b, v51
	v_exp_f32_e32 v40, v40
	s_nop 0
	v_add_f32_e32 v40, 1.0, v40
	v_rcp_f32_e32 v40, v40
	s_nop 0
	v_mul_f32_e32 v40, v51, v40
	v_mul_f32_e32 v49, v50, v40
	v_pk_mul_f32 v[40:41], v[44:45], v[48:49] op_sel_hi:[1,0]
	s_nop 0
	v_mul_f32_e32 v44, 0xbfb8aa3b, v41
	v_exp_f32_e32 v44, v44
	s_nop 0
	v_add_f32_e32 v44, 1.0, v44
	v_rcp_f32_e32 v44, v44
	s_nop 0
	v_mul_f32_e32 v41, v41, v44
	v_mul_f32_e32 v44, v40, v41
	v_mov_b32_e32 v40, v42
	v_mov_b32_e32 v41, v46
	v_pk_mul_f32 v[40:41], v[40:41], v[48:49] op_sel_hi:[1,0]
	v_mov_b32_e32 v46, v43
	v_mul_f32_e32 v42, 0xbfb8aa3b, v41
	v_exp_f32_e32 v42, v42
	s_nop 0
	v_add_f32_e32 v42, 1.0, v42
	v_rcp_f32_e32 v42, v42
	s_nop 0
	v_mul_f32_e32 v41, v41, v42
	v_mul_f32_e32 v42, v40, v41
	v_pk_mul_f32 v[40:41], v[46:47], v[48:49] op_sel_hi:[1,0]
	s_nop 0
	v_mul_f32_e32 v43, 0xbfb8aa3b, v41
	v_exp_f32_e32 v43, v43
	s_nop 0
	v_add_f32_e32 v43, 1.0, v43
	v_rcp_f32_e32 v43, v43
	s_nop 0
	v_mul_f32_e32 v41, v41, v43
	v_mul_f32_e32 v43, v40, v41
	v_mov_b32_e32 v40, v32
	v_mov_b32_e32 v41, v36
	v_pk_mul_f32 v[40:41], v[40:41], v[48:49] op_sel_hi:[1,0]
	v_mov_b32_e32 v36, v33
	v_mul_f32_e32 v32, 0xbfb8aa3b, v41
	v_exp_f32_e32 v32, v32
	s_nop 0
	v_add_f32_e32 v32, 1.0, v32
	v_rcp_f32_e32 v32, v32
	s_nop 0
	v_mul_f32_e32 v32, v41, v32
	v_mul_f32_e32 v40, v40, v32
	v_pk_mul_f32 v[32:33], v[36:37], v[48:49] op_sel_hi:[1,0]
	s_nop 0
	v_mul_f32_e32 v36, 0xbfb8aa3b, v33
	v_exp_f32_e32 v36, v36
	s_nop 0
	v_add_f32_e32 v36, 1.0, v36
	v_rcp_f32_e32 v36, v36
	s_nop 0
	v_mul_f32_e32 v33, v33, v36
	v_mul_f32_e32 v36, v32, v33
	v_mov_b32_e32 v32, v34
	v_mov_b32_e32 v33, v38
	v_pk_mul_f32 v[32:33], v[32:33], v[48:49] op_sel_hi:[1,0]
	v_mov_b32_e32 v38, v35
	v_mul_f32_e32 v34, 0xbfb8aa3b, v33
	v_exp_f32_e32 v34, v34
	s_nop 0
	v_add_f32_e32 v34, 1.0, v34
	v_rcp_f32_e32 v34, v34
	s_nop 0
	v_mul_f32_e32 v33, v33, v34
	v_mul_f32_e32 v37, v32, v33
	v_pk_mul_f32 v[32:33], v[38:39], v[48:49] op_sel_hi:[1,0]
	s_nop 0
	v_mul_f32_e32 v34, 0xbfb8aa3b, v33
	v_exp_f32_e32 v34, v34
	s_nop 0
	v_add_f32_e32 v34, 1.0, v34
	v_rcp_f32_e32 v34, v34
	s_nop 0
	v_mul_f32_e32 v33, v33, v34
	v_mul_f32_e32 v35, v32, v33
	v_cvt_pk_bf16_f32 v32, v49, v44
	v_cvt_pk_bf16_f32 v33, v42, v43
	v_cvt_pk_bf16_f32 v34, v40, v36
	v_add_co_u32_e32 v36, vcc, s20, v112
	v_cvt_pk_bf16_f32 v35, v37, v35
	s_mov_b32 s20, 0x1b8000
	s_nop 0
	v_addc_co_u32_e32 v37, vcc, 0, v113, vcc
	global_store_dwordx4 v[36:37], v[32:35], off
	ds_read_b32 v32, v155 offset:640
	s_nop 0
	v_mov_b32_e32 v34, v24
	v_mov_b32_e32 v35, v28
	v_mov_b32_e32 v28, v25
	s_waitcnt lgkmcnt(0)
; __device__ __forceinline__ float sigmoidf_(float x) { return __builtin_amdgcn_rcpf(1.0f + __expf(-x)); }
; __device__ __forceinline__ u32x4 pack8(const f32x4& a, const f32x4& b) { u32x4 w; w.x = cvt_pk_bf16(a[0], a[1]); w.y = cvt_pk_bf16(a[2], a[3]); w.z = cvt_pk_bf16(b[0], b[1]); w.w = cvt_pk_bf16(b[2], b[3]); return w; }
;     __device__ __forceinline__ void operator()(const f32x4 (&acc)[2][2][4][2], const Unit& u, int wr, int wc, int fr, int fq) const {
;     ...
; #pragma unroll
;         for (int ai = 0; ai < 2; ++ai)
; #pragma unroll
;             for (int m = 0; m < 4; ++m) { const size_t row = (size_t)u.pm * BM + ai * HALF + wr * 64 + m * 16 + fr;
;                 const float rs = tab[ai * HALF + wr * 64 + m * 16 + fr];
;                 f32x4 h[2];
; #pragma unroll
;                 for (int n = 0; n < 2; ++n) { const f32x4 g = acc[ai][0][m][n] * rs, up = acc[ai][1][m][n] * rs;
; #pragma unroll
;                     for (int j = 0; j < 4; ++j) h[n][j] = g[j] * sigmoidf_(g[j]) * up[j]; }
;                 *(u32x4*)(H + row * 5632 + u.pn * HALF + wc * 32 + fq * 8) = pack8(h[0], h[1]); }
; template <class Epi, class Sched, bool ALIGN_EPI = false, bool SP2 = false>
; __device__ __forceinline__ void gemm_phase(PG8_LAS unsigned char* lds, const Gemm g, const Sched& S, const Epi& E) {
;     ...
;         if constexpr (!Epi::AFTER_DRAIN) { E(acc, cur, wr, wc, fr, fq); S.done(cur); }
;         if (!has_next) break;
	v_pk_mul_f32 v[34:35], v[34:35], v[32:33] op_sel_hi:[1,0]
	s_nop 0
	v_mul_f32_e32 v24, 0xbfb8aa3b, v35
	v_exp_f32_e32 v24, v24
	s_nop 0
	v_add_f32_e32 v24, 1.0, v24
	v_rcp_f32_e32 v24, v24
	s_nop 0
	v_mul_f32_e32 v24, v35, v24
	v_mul_f32_e32 v33, v34, v24
	v_pk_mul_f32 v[24:25], v[28:29], v[32:33] op_sel_hi:[1,0]
	s_nop 0
	v_mul_f32_e32 v28, 0xbfb8aa3b, v25
	v_exp_f32_e32 v28, v28
	s_nop 0
	v_add_f32_e32 v28, 1.0, v28
	v_rcp_f32_e32 v28, v28
	s_nop 0
	v_mul_f32_e32 v25, v25, v28
	v_mul_f32_e32 v28, v24, v25
	v_mov_b32_e32 v24, v26
	v_mov_b32_e32 v25, v30
	v_pk_mul_f32 v[24:25], v[24:25], v[32:33] op_sel_hi:[1,0]
	v_mov_b32_e32 v30, v27
	v_mul_f32_e32 v26, 0xbfb8aa3b, v25
	v_exp_f32_e32 v26, v26
	s_nop 0
	v_add_f32_e32 v26, 1.0, v26
	v_rcp_f32_e32 v26, v26
	s_nop 0
	v_mul_f32_e32 v25, v25, v26
	v_mul_f32_e32 v26, v24, v25
	v_pk_mul_f32 v[24:25], v[30:31], v[32:33] op_sel_hi:[1,0]
	s_nop 0
	v_mul_f32_e32 v27, 0xbfb8aa3b, v25
	v_exp_f32_e32 v27, v27
	s_nop 0
	v_add_f32_e32 v27, 1.0, v27
	v_rcp_f32_e32 v27, v27
	s_nop 0
	v_mul_f32_e32 v25, v25, v27
	v_mul_f32_e32 v27, v24, v25
	v_mov_b32_e32 v24, v16
	v_mov_b32_e32 v25, v20
	v_pk_mul_f32 v[24:25], v[24:25], v[32:33] op_sel_hi:[1,0]
	v_mov_b32_e32 v20, v17
	v_mul_f32_e32 v16, 0xbfb8aa3b, v25
	v_exp_f32_e32 v16, v16
	s_nop 0
	v_add_f32_e32 v16, 1.0, v16
	v_rcp_f32_e32 v16, v16
	s_nop 0
	v_mul_f32_e32 v16, v25, v16
	v_mul_f32_e32 v24, v24, v16
	v_pk_mul_f32 v[16:17], v[20:21], v[32:33] op_sel_hi:[1,0]
	s_nop 0
	v_mul_f32_e32 v20, 0xbfb8aa3b, v17
	v_exp_f32_e32 v20, v20
	s_nop 0
	v_add_f32_e32 v20, 1.0, v20
	v_rcp_f32_e32 v20, v20
	s_nop 0
	v_mul_f32_e32 v17, v17, v20
	v_mul_f32_e32 v20, v16, v17
	v_mov_b32_e32 v16, v18
	v_mov_b32_e32 v17, v22
	v_pk_mul_f32 v[16:17], v[16:17], v[32:33] op_sel_hi:[1,0]
	v_mov_b32_e32 v22, v19
	v_mul_f32_e32 v18, 0xbfb8aa3b, v17
	v_exp_f32_e32 v18, v18
	s_nop 0
	v_add_f32_e32 v18, 1.0, v18
	v_rcp_f32_e32 v18, v18
	s_nop 0
	v_mul_f32_e32 v17, v17, v18
	v_mul_f32_e32 v21, v16, v17
	v_pk_mul_f32 v[16:17], v[22:23], v[32:33] op_sel_hi:[1,0]
	s_nop 0
	v_mul_f32_e32 v18, 0xbfb8aa3b, v17
	v_exp_f32_e32 v18, v18
	s_nop 0
	v_add_f32_e32 v18, 1.0, v18
	v_rcp_f32_e32 v18, v18
	s_nop 0
	v_mul_f32_e32 v17, v17, v18
	v_mul_f32_e32 v19, v16, v17
	v_cvt_pk_bf16_f32 v16, v33, v28
	v_cvt_pk_bf16_f32 v17, v26, v27
	v_cvt_pk_bf16_f32 v18, v24, v20
	v_add_co_u32_e32 v20, vcc, s20, v112
	v_cvt_pk_bf16_f32 v19, v21, v19
	s_mov_b64 s[20:21], -1
	s_nop 0
	v_addc_co_u32_e32 v21, vcc, 0, v113, vcc
	global_store_dwordx4 v[20:21], v[16:19], off
	ds_read_b32 v16, v155 offset:704
	s_nop 0
	v_mov_b32_e32 v18, v8
	v_mov_b32_e32 v19, v12
	v_mov_b32_e32 v12, v9
	s_waitcnt lgkmcnt(0)
	v_pk_mul_f32 v[18:19], v[18:19], v[16:17] op_sel_hi:[1,0]
	s_nop 0
	v_mul_f32_e32 v8, 0xbfb8aa3b, v19
	v_exp_f32_e32 v8, v8
	s_nop 0
	v_add_f32_e32 v8, 1.0, v8
	v_rcp_f32_e32 v8, v8
	s_nop 0
	v_mul_f32_e32 v8, v19, v8
	v_mul_f32_e32 v17, v18, v8
	v_pk_mul_f32 v[8:9], v[12:13], v[16:17] op_sel_hi:[1,0]
	s_nop 0
	v_mul_f32_e32 v12, 0xbfb8aa3b, v9
	v_exp_f32_e32 v12, v12
	s_nop 0
	v_add_f32_e32 v12, 1.0, v12
	v_rcp_f32_e32 v12, v12
	s_nop 0
	v_mul_f32_e32 v9, v9, v12
	v_mul_f32_e32 v12, v8, v9
	v_mov_b32_e32 v8, v10
	v_mov_b32_e32 v9, v14
	v_pk_mul_f32 v[8:9], v[8:9], v[16:17] op_sel_hi:[1,0]
	v_mov_b32_e32 v14, v11
	v_mul_f32_e32 v10, 0xbfb8aa3b, v9
	v_exp_f32_e32 v10, v10
	s_nop 0
	v_add_f32_e32 v10, 1.0, v10
	v_rcp_f32_e32 v10, v10
	s_nop 0
	v_mul_f32_e32 v9, v9, v10
	v_mul_f32_e32 v10, v8, v9
	v_pk_mul_f32 v[8:9], v[14:15], v[16:17] op_sel_hi:[1,0]
	s_nop 0
	v_mul_f32_e32 v11, 0xbfb8aa3b, v9
	v_exp_f32_e32 v11, v11
	s_nop 0
	v_add_f32_e32 v11, 1.0, v11
	v_rcp_f32_e32 v11, v11
	s_nop 0
	v_mul_f32_e32 v9, v9, v11
	v_mul_f32_e32 v11, v8, v9
	v_mov_b32_e32 v8, v0
	v_mov_b32_e32 v9, v4
	v_pk_mul_f32 v[8:9], v[8:9], v[16:17] op_sel_hi:[1,0]
	v_mov_b32_e32 v4, v1
	v_mul_f32_e32 v0, 0xbfb8aa3b, v9
	v_exp_f32_e32 v0, v0
	s_nop 0
	v_add_f32_e32 v0, 1.0, v0
	v_rcp_f32_e32 v0, v0
	s_nop 0
	v_mul_f32_e32 v0, v9, v0
	v_mul_f32_e32 v8, v8, v0
	v_pk_mul_f32 v[0:1], v[4:5], v[16:17] op_sel_hi:[1,0]
	s_nop 0
	v_mul_f32_e32 v4, 0xbfb8aa3b, v1
	v_exp_f32_e32 v4, v4
	s_nop 0
	v_add_f32_e32 v4, 1.0, v4
	v_rcp_f32_e32 v4, v4
	s_nop 0
	v_mul_f32_e32 v1, v1, v4
	v_mul_f32_e32 v4, v0, v1
	v_mov_b32_e32 v0, v2
	v_mov_b32_e32 v1, v6
	v_pk_mul_f32 v[0:1], v[0:1], v[16:17] op_sel_hi:[1,0]
	v_mov_b32_e32 v6, v3
	v_mul_f32_e32 v2, 0xbfb8aa3b, v1
	v_exp_f32_e32 v2, v2
	s_nop 0
	v_add_f32_e32 v2, 1.0, v2
	v_rcp_f32_e32 v2, v2
	s_nop 0
	v_mul_f32_e32 v1, v1, v2
	v_mul_f32_e32 v5, v0, v1
	v_pk_mul_f32 v[0:1], v[6:7], v[16:17] op_sel_hi:[1,0]
	s_nop 0
	v_mul_f32_e32 v2, 0xbfb8aa3b, v1
	v_exp_f32_e32 v2, v2
	s_nop 0
	v_add_f32_e32 v2, 1.0, v2
	v_rcp_f32_e32 v2, v2
	s_nop 0
	v_mul_f32_e32 v1, v1, v2
	v_mul_f32_e32 v3, v0, v1
	v_cvt_pk_bf16_f32 v0, v17, v12
	v_cvt_pk_bf16_f32 v1, v10, v11
	v_cvt_pk_bf16_f32 v2, v8, v4
	v_add_co_u32_e32 v4, vcc, 0x1e4000, v112
	v_cvt_pk_bf16_f32 v3, v5, v3
	s_nop 1
	v_addc_co_u32_e32 v5, vcc, 0, v113, vcc
	s_andn2_b64 vcc, exec, s[36:37]
	global_store_dwordx4 v[4:5], v[0:3], off
.Lp7_epi_tail:
	s_cbranch_vccnz .LBB0_1820
	s_andn2_b64 vcc, exec, s[14:15]
	s_cbranch_vccnz .LBB0_1819
	s_barrier
	s_branch .LBB0_1819
.Lp7_half_dispatch:
	s_cmp_ge_u32 s72, 128
	s_cbranch_scc1 .Lp7h1_loop
; #define PG8_STAGE(bufoff, gbase, voff) do { _Pragma("unroll") for (int _i = 0; _i < 2; ++_i) \
;         __builtin_amdgcn_global_load_lds((const unsigned*)((const char*)(gbase) + (voff)[_i]), (PG8_LAS unsigned*)(lds + (bufoff) + ldsw + _i * 8192), 16, 0, 0); } while (0)
; #define PG8_LDA(dst, b, h) do { _Pragma("unroll") for (int m = 0; m < 4; ++m) _Pragma("unroll") for (int k = 0; k < 2; ++k) dst[m][k] = *(const PG8_LAS bf16x8*)(lds + PG8_SA(b, h) + aoff + m * 2048 + k * 1024); } while (0)
; #define PG8_WAIT_V(n) asm volatile("s_waitcnt vmcnt(" #n ")" ::: "memory")
; #define PG8_BAR __builtin_amdgcn_s_barrier()
; template <class Epi, class Sched, bool ALIGN_EPI = false, bool SP2 = false>
; __device__ __forceinline__ void gemm_phase(PG8_LAS unsigned char* lds, const Gemm g, const Sched& S, const Epi& E) {
;     ...
;         for (int t = 0; t < nt; t += 2) {
;             const bool last = (t == nt - 2);
;             if constexpr (Epi::HAS_MID) { if (t == E.mid_t) E.mid(acc, cur, wr, wc, fr, fq); }
;             const char* a1 = cA + (size_t)(t + 1) * kstep;
;             const char* a2 = last ? nA : cA + (size_t)(t + 2) * kstep; const char* b2 = last ? nB : cB + (size_t)(t + 2) * kstep;
;             const char* a3 = a2 + kstep; const char* b3 = b2 + kstep;
;             if (last && has_next) S.a_ready(nxt);
;             if constexpr (SP2) {
;             PG8_LDB(B0, 0, 0); PG8_LDB(B1, 0, 1); PG8_SCHED; PG8_LDA(At, 0, 0); PG8_STAGE(PG8_SA(1, 1), a1 + hstepA, voffA);
;             PG8_WAIT_V(8); PG8_WAIT_L(0); PG8_BAR; PG8_MMA(0, 0, At, B0); PG8_MMA(0, 1, At, B1); PG8_BAR; PG8_SCHED;
;             PG8_LDA(At, 0, 1); PG8_STAGE(PG8_SB(0, 0), b2, voffB); PG8_STAGE(PG8_SB(0, 1), b2 + hstepB, voffB); PG8_STAGE(PG8_SA(0, 0), a2, voffA);
;             PG8_WAIT_V(8); PG8_WAIT_L(0); PG8_BAR; PG8_MMA(1, 0, At, B0); PG8_MMA(1, 1, At, B1); PG8_BAR; PG8_SCHED;
;             PG8_LDB(B0, 1, 0); PG8_LDB(B1, 1, 1); PG8_SCHED; PG8_LDA(At, 1, 0); PG8_STAGE(PG8_SA(0, 1), a2 + hstepA, voffA);
;             PG8_WAIT_V(8); PG8_WAIT_L(0); PG8_BAR; PG8_MMA(0, 0, At, B0); PG8_MMA(0, 1, At, B1); PG8_BAR; PG8_SCHED;
;             PG8_LDA(At, 1, 1); PG8_STAGE(PG8_SB(1, 0), b3, voffB); PG8_STAGE(PG8_SB(1, 1), b3 + hstepB, voffB); PG8_STAGE(PG8_SA(1, 0), a3, voffA);
;             PG8_WAIT_V(8); PG8_WAIT_L(0); PG8_BAR; PG8_MMA(1, 0, At, B0); PG8_MMA(1, 1, At, B1); PG8_BAR; PG8_SCHED;
.Lp7h0_loop:
	ds_read_b128 v[144:147], v151
	ds_read_b128 v[156:159], v151 offset:1024
	ds_read_b128 v[160:163], v151 offset:2048
	ds_read_b128 v[164:167], v151 offset:3072
	ds_read_b128 v[168:171], v152
	ds_read_b128 v[172:175], v152 offset:1024
	ds_read_b128 v[176:179], v152 offset:2048
	ds_read_b128 v[180:183], v152 offset:3072
	s_add_u32 s34, s30, 0xfff80080
	s_addc_u32 s35, s31, -1
	s_cmp_eq_u32 s62, 28
	s_cselect_b32 s39, s21, s35
	s_cselect_b32 s38, s25, s34
	s_cselect_b32 s35, s23, s61
	s_cselect_b32 s34, s59, s60
	v_lshl_add_u64 v[216:217], s[30:31], 0, v[136:137]
	s_add_i32 m0, s6, 0xc000
	ds_read_b128 v[184:187], v153
	ds_read_b128 v[188:191], v153 offset:1024
	ds_read_b128 v[192:195], v153 offset:2048
	ds_read_b128 v[196:199], v153 offset:3072
	ds_read_b128 v[200:203], v153 offset:4096
	ds_read_b128 v[204:207], v153 offset:5120
	ds_read_b128 v[208:211], v153 offset:6144
	ds_read_b128 v[212:215], v153 offset:7168
	global_load_lds_dwordx4 v[216:217], off
	v_lshl_add_u64 v[216:217], s[30:31], 0, v[138:139]
	s_add_i32 m0, s6, 0xe000
	s_nop 0
	global_load_lds_dwordx4 v[216:217], off
	s_waitcnt vmcnt(8)
	s_waitcnt lgkmcnt(0)
	s_barrier
	s_setprio 1
	s_waitcnt lgkmcnt(0)
	v_mfma_f32_16x16x32_bf16 v[124:127], v[144:147], v[184:187], v[124:127]
	v_mfma_f32_16x16x32_bf16 v[116:119], v[160:163], v[184:187], v[116:119]
	v_mfma_f32_16x16x32_bf16 v[108:111], v[144:147], v[192:195], v[108:111]
	v_mfma_f32_16x16x32_bf16 v[100:103], v[160:163], v[192:195], v[100:103]
	v_mfma_f32_16x16x32_bf16 v[92:95], v[144:147], v[200:203], v[92:95]
	v_mfma_f32_16x16x32_bf16 v[84:87], v[160:163], v[200:203], v[84:87]
	v_mfma_f32_16x16x32_bf16 v[76:79], v[144:147], v[208:211], v[76:79]
	v_mfma_f32_16x16x32_bf16 v[68:71], v[160:163], v[208:211], v[68:71]
	v_mfma_f32_16x16x32_bf16 v[124:127], v[156:159], v[188:191], v[124:127]
	v_mfma_f32_16x16x32_bf16 v[116:119], v[164:167], v[188:191], v[116:119]
	v_mfma_f32_16x16x32_bf16 v[108:111], v[156:159], v[196:199], v[108:111]
	v_mfma_f32_16x16x32_bf16 v[100:103], v[164:167], v[196:199], v[100:103]
	v_mfma_f32_16x16x32_bf16 v[92:95], v[156:159], v[204:207], v[92:95]
	v_mfma_f32_16x16x32_bf16 v[84:87], v[164:167], v[204:207], v[84:87]
	v_mfma_f32_16x16x32_bf16 v[76:79], v[156:159], v[212:215], v[76:79]
	v_mfma_f32_16x16x32_bf16 v[68:71], v[164:167], v[212:215], v[68:71]
	s_setprio 0
	s_setprio 1
	v_mfma_f32_16x16x32_bf16 v[120:123], v[168:171], v[184:187], v[120:123]
	v_mfma_f32_16x16x32_bf16 v[112:115], v[176:179], v[184:187], v[112:115]
	v_mfma_f32_16x16x32_bf16 v[104:107], v[168:171], v[192:195], v[104:107]
	v_mfma_f32_16x16x32_bf16 v[96:99], v[176:179], v[192:195], v[96:99]
	v_mfma_f32_16x16x32_bf16 v[88:91], v[168:171], v[200:203], v[88:91]
	v_mfma_f32_16x16x32_bf16 v[80:83], v[176:179], v[200:203], v[80:83]
	v_mfma_f32_16x16x32_bf16 v[72:75], v[168:171], v[208:211], v[72:75]
	v_mfma_f32_16x16x32_bf16 v[64:67], v[176:179], v[208:211], v[64:67]
	v_mfma_f32_16x16x32_bf16 v[120:123], v[172:175], v[188:191], v[120:123]
	v_mfma_f32_16x16x32_bf16 v[112:115], v[180:183], v[188:191], v[112:115]
	v_mfma_f32_16x16x32_bf16 v[104:107], v[172:175], v[196:199], v[104:107]
	v_mfma_f32_16x16x32_bf16 v[96:99], v[180:183], v[196:199], v[96:99]
	v_mfma_f32_16x16x32_bf16 v[88:91], v[172:175], v[204:207], v[88:91]
	v_mfma_f32_16x16x32_bf16 v[80:83], v[180:183], v[204:207], v[80:83]
	v_mfma_f32_16x16x32_bf16 v[72:75], v[172:175], v[212:215], v[72:75]
	v_mfma_f32_16x16x32_bf16 v[64:67], v[180:183], v[212:215], v[64:67]
	s_setprio 0
	s_barrier
	s_add_i32 s63, s53, s4
	v_lshl_add_u64 v[216:217], s[34:35], 0, v[132:133]
	s_mov_b32 m0, s63
	global_load_lds_dwordx4 v[216:217], off
	s_add_i32 m0, s63, 0x2000
	s_add_u32 s64, s34, 0x80000
	v_lshl_add_u64 v[218:219], s[34:35], 0, v[128:129]
	s_addc_u32 s65, s35, 0
	s_add_i32 s63, s54, s4
	global_load_lds_dwordx4 v[218:219], off
	v_lshl_add_u64 v[220:221], s[64:65], 0, v[132:133]
	s_mov_b32 m0, s63
	v_lshl_add_u64 v[222:223], s[38:39], 0, v[130:131]
	global_load_lds_dwordx4 v[220:221], off
	v_lshl_add_u64 v[220:221], s[64:65], 0, v[128:129]
	s_add_i32 m0, s63, 0x2000
	s_nop 0
	global_load_lds_dwordx4 v[220:221], off
	v_lshl_add_u64 v[220:221], s[38:39], 0, v[134:135]
	s_mov_b32 m0, s6
	s_nop 0
	global_load_lds_dwordx4 v[220:221], off
	s_mov_b32 m0, s7
	s_nop 0
	global_load_lds_dwordx4 v[222:223], off
	s_waitcnt vmcnt(8)
	s_waitcnt lgkmcnt(0)
	s_barrier
	s_setprio 1
	s_waitcnt lgkmcnt(0)
	s_setprio 0
	s_setprio 1
	s_setprio 0
	s_barrier
	s_add_i32 s63, 0, 0x18000
	v_add_u32_e32 v155, s63, v150
	s_add_i32 s64, 0, 0x1c000
	ds_read_b128 v[144:147], v155
	ds_read_b128 v[156:159], v155 offset:1024
	ds_read_b128 v[160:163], v155 offset:2048
	ds_read_b128 v[164:167], v155 offset:3072
	v_add_u32_e32 v155, s64, v150
	ds_read_b128 v[168:171], v155
	ds_read_b128 v[172:175], v155 offset:1024
	ds_read_b128 v[176:179], v155 offset:2048
	ds_read_b128 v[180:183], v155 offset:3072
	s_add_u32 s38, s38, 0x80000
	s_addc_u32 s39, s39, 0
	s_mov_b32 m0, s41
	v_lshl_add_u64 v[224:225], s[38:39], 0, v[134:135]
	ds_read_b128 v[184:187], v153 offset:32768
	ds_read_b128 v[188:191], v153 offset:33792
	ds_read_b128 v[192:195], v153 offset:34816
	ds_read_b128 v[196:199], v153 offset:35840
	ds_read_b128 v[200:203], v153 offset:36864
	ds_read_b128 v[204:207], v153 offset:37888
	ds_read_b128 v[208:211], v153 offset:38912
	ds_read_b128 v[212:215], v153 offset:39936
	global_load_lds_dwordx4 v[224:225], off
	v_lshl_add_u64 v[224:225], s[38:39], 0, v[130:131]
	s_mov_b32 m0, s42
	s_nop 0
	global_load_lds_dwordx4 v[224:225], off
	s_waitcnt vmcnt(8)
	s_waitcnt lgkmcnt(0)
	s_barrier
; #define PG8_STAGE(bufoff, gbase, voff) do { _Pragma("unroll") for (int _i = 0; _i < 2; ++_i) \
;         __builtin_amdgcn_global_load_lds((const unsigned*)((const char*)(gbase) + (voff)[_i]), (PG8_LAS unsigned*)(lds + (bufoff) + ldsw + _i * 8192), 16, 0, 0); } while (0)
; #define PG8_LDA(dst, b, h) do { _Pragma("unroll") for (int m = 0; m < 4; ++m) _Pragma("unroll") for (int k = 0; k < 2; ++k) dst[m][k] = *(const PG8_LAS bf16x8*)(lds + PG8_SA(b, h) + aoff + m * 2048 + k * 1024); } while (0)
; #define PG8_WAIT_V(n) asm volatile("s_waitcnt vmcnt(" #n ")" ::: "memory")
; #define PG8_BAR __builtin_amdgcn_s_barrier()
; template <class Epi, class Sched, bool ALIGN_EPI = false, bool SP2 = false>
; __device__ __forceinline__ void gemm_phase(PG8_LAS unsigned char* lds, const Gemm g, const Sched& S, const Epi& E) {
;     ...
;         for (int t = 0; t < nt; t += 2) {
;             const bool last = (t == nt - 2);
;             if constexpr (Epi::HAS_MID) { if (t == E.mid_t) E.mid(acc, cur, wr, wc, fr, fq); }
;             const char* a1 = cA + (size_t)(t + 1) * kstep;
;             const char* a2 = last ? nA : cA + (size_t)(t + 2) * kstep; const char* b2 = last ? nB : cB + (size_t)(t + 2) * kstep;
;             const char* a3 = a2 + kstep; const char* b3 = b2 + kstep;
;             if (last && has_next) S.a_ready(nxt);
;             if constexpr (SP2) {
;             PG8_LDB(B0, 0, 0); PG8_LDB(B1, 0, 1); PG8_SCHED; PG8_LDA(At, 0, 0); PG8_STAGE(PG8_SA(1, 1), a1 + hstepA, voffA);
;             PG8_WAIT_V(8); PG8_WAIT_L(0); PG8_BAR; PG8_MMA(0, 0, At, B0); PG8_MMA(0, 1, At, B1); PG8_BAR; PG8_SCHED;
;             PG8_LDA(At, 0, 1); PG8_STAGE(PG8_SB(0, 0), b2, voffB); PG8_STAGE(PG8_SB(0, 1), b2 + hstepB, voffB); PG8_STAGE(PG8_SA(0, 0), a2, voffA);
;             PG8_WAIT_V(8); PG8_WAIT_L(0); PG8_BAR; PG8_MMA(1, 0, At, B0); PG8_MMA(1, 1, At, B1); PG8_BAR; PG8_SCHED;
;             PG8_LDB(B0, 1, 0); PG8_LDB(B1, 1, 1); PG8_SCHED; PG8_LDA(At, 1, 0); PG8_STAGE(PG8_SA(0, 1), a2 + hstepA, voffA);
;             PG8_WAIT_V(8); PG8_WAIT_L(0); PG8_BAR; PG8_MMA(0, 0, At, B0); PG8_MMA(0, 1, At, B1); PG8_BAR; PG8_SCHED;
;             PG8_LDA(At, 1, 1); PG8_STAGE(PG8_SB(1, 0), b3, voffB); PG8_STAGE(PG8_SB(1, 1), b3 + hstepB, voffB); PG8_STAGE(PG8_SA(1, 0), a3, voffA);
;             PG8_WAIT_V(8); PG8_WAIT_L(0); PG8_BAR; PG8_MMA(1, 0, At, B0); PG8_MMA(1, 1, At, B1); PG8_BAR; PG8_SCHED;
	s_setprio 1
	s_waitcnt lgkmcnt(0)
	v_mfma_f32_16x16x32_bf16 v[124:127], v[144:147], v[184:187], v[124:127]
	v_mfma_f32_16x16x32_bf16 v[116:119], v[160:163], v[184:187], v[116:119]
	v_mfma_f32_16x16x32_bf16 v[108:111], v[144:147], v[192:195], v[108:111]
	v_mfma_f32_16x16x32_bf16 v[100:103], v[160:163], v[192:195], v[100:103]
	v_mfma_f32_16x16x32_bf16 v[92:95], v[144:147], v[200:203], v[92:95]
	v_mfma_f32_16x16x32_bf16 v[84:87], v[160:163], v[200:203], v[84:87]
	v_mfma_f32_16x16x32_bf16 v[76:79], v[144:147], v[208:211], v[76:79]
	v_mfma_f32_16x16x32_bf16 v[68:71], v[160:163], v[208:211], v[68:71]
	v_mfma_f32_16x16x32_bf16 v[124:127], v[156:159], v[188:191], v[124:127]
	v_mfma_f32_16x16x32_bf16 v[116:119], v[164:167], v[188:191], v[116:119]
	v_mfma_f32_16x16x32_bf16 v[108:111], v[156:159], v[196:199], v[108:111]
	v_mfma_f32_16x16x32_bf16 v[100:103], v[164:167], v[196:199], v[100:103]
	v_mfma_f32_16x16x32_bf16 v[92:95], v[156:159], v[204:207], v[92:95]
	v_mfma_f32_16x16x32_bf16 v[84:87], v[164:167], v[204:207], v[84:87]
	v_mfma_f32_16x16x32_bf16 v[76:79], v[156:159], v[212:215], v[76:79]
	v_mfma_f32_16x16x32_bf16 v[68:71], v[164:167], v[212:215], v[68:71]
	s_setprio 0
	s_setprio 1
	v_mfma_f32_16x16x32_bf16 v[120:123], v[168:171], v[184:187], v[120:123]
	v_mfma_f32_16x16x32_bf16 v[112:115], v[176:179], v[184:187], v[112:115]
	v_mfma_f32_16x16x32_bf16 v[104:107], v[168:171], v[192:195], v[104:107]
	v_mfma_f32_16x16x32_bf16 v[96:99], v[176:179], v[192:195], v[96:99]
	v_mfma_f32_16x16x32_bf16 v[88:91], v[168:171], v[200:203], v[88:91]
	v_mfma_f32_16x16x32_bf16 v[80:83], v[176:179], v[200:203], v[80:83]
	v_mfma_f32_16x16x32_bf16 v[72:75], v[168:171], v[208:211], v[72:75]
	v_mfma_f32_16x16x32_bf16 v[64:67], v[176:179], v[208:211], v[64:67]
	v_mfma_f32_16x16x32_bf16 v[120:123], v[172:175], v[188:191], v[120:123]
	v_mfma_f32_16x16x32_bf16 v[112:115], v[180:183], v[188:191], v[112:115]
	v_mfma_f32_16x16x32_bf16 v[104:107], v[172:175], v[196:199], v[104:107]
	v_mfma_f32_16x16x32_bf16 v[96:99], v[180:183], v[196:199], v[96:99]
	v_mfma_f32_16x16x32_bf16 v[88:91], v[172:175], v[204:207], v[88:91]
	v_mfma_f32_16x16x32_bf16 v[80:83], v[180:183], v[204:207], v[80:83]
	v_mfma_f32_16x16x32_bf16 v[72:75], v[172:175], v[212:215], v[72:75]
	v_mfma_f32_16x16x32_bf16 v[64:67], v[180:183], v[212:215], v[64:67]
	s_setprio 0
	s_barrier
	s_add_i32 s38, s63, s4
	v_lshl_add_u64 v[216:217], v[216:217], 0, s[16:17]
	s_mov_b32 m0, s38
	global_load_lds_dwordx4 v[216:217], off
	s_add_i32 m0, s38, 0x2000
	s_add_u32 s34, s34, 0x80080
	v_lshl_add_u64 v[216:217], v[218:219], 0, s[16:17]
	s_addc_u32 s35, s35, 0
	s_add_i32 s38, s64, s4
	global_load_lds_dwordx4 v[216:217], off
	v_lshl_add_u64 v[216:217], s[34:35], 0, v[132:133]
	s_mov_b32 m0, s38
	s_nop 0
	global_load_lds_dwordx4 v[216:217], off
	v_lshl_add_u64 v[216:217], s[34:35], 0, v[128:129]
	s_add_i32 m0, s38, 0x2000
	s_nop 0
	global_load_lds_dwordx4 v[216:217], off
	v_lshl_add_u64 v[216:217], v[220:221], 0, s[16:17]
	s_mov_b32 m0, s46
	s_nop 0
	global_load_lds_dwordx4 v[216:217], off
	v_lshl_add_u64 v[216:217], v[222:223], 0, s[16:17]
	s_mov_b32 m0, s47
	s_nop 0
	global_load_lds_dwordx4 v[216:217], off
	s_waitcnt vmcnt(8)
	s_waitcnt lgkmcnt(0)
	s_barrier
	s_setprio 1
	s_waitcnt lgkmcnt(0)
	s_setprio 0
	s_setprio 1
	s_setprio 0
	s_barrier
	s_add_i32 s62, s62, 2
	s_add_u32 s30, s30, 0x100
	s_addc_u32 s31, s31, 0
	s_add_u32 s60, s60, 0x100
	s_addc_u32 s61, s61, 0
	s_cmp_gt_u32 s62, 29
	s_cbranch_scc0 .Lp7h0_loop
	s_branch .Lp7_after_loop
.Lp7h1_loop:
	ds_read_b128 v[144:147], v151
	ds_read_b128 v[156:159], v151 offset:1024
	ds_read_b128 v[160:163], v151 offset:2048
	ds_read_b128 v[164:167], v151 offset:3072
	ds_read_b128 v[168:171], v152
	ds_read_b128 v[172:175], v152 offset:1024
	ds_read_b128 v[176:179], v152 offset:2048
	ds_read_b128 v[180:183], v152 offset:3072
	s_add_u32 s34, s30, 0xfff80080
	s_addc_u32 s35, s31, -1
	s_cmp_eq_u32 s62, 28
	s_cselect_b32 s39, s21, s35
	s_cselect_b32 s38, s25, s34
	s_cselect_b32 s35, s23, s61
	s_cselect_b32 s34, s59, s60
	v_lshl_add_u64 v[216:217], s[30:31], 0, v[136:137]
	s_add_i32 m0, s6, 0xc000
	global_load_lds_dwordx4 v[216:217], off
	v_lshl_add_u64 v[216:217], s[30:31], 0, v[138:139]
	s_add_i32 m0, s6, 0xe000
	s_nop 0
	global_load_lds_dwordx4 v[216:217], off
	s_waitcnt vmcnt(8)
	s_waitcnt lgkmcnt(0)
	s_barrier
	s_setprio 1
	s_waitcnt lgkmcnt(0)
	s_setprio 0
	s_setprio 1
	s_setprio 0
	s_barrier
	s_add_i32 s63, s53, s4
	v_lshl_add_u64 v[216:217], s[34:35], 0, v[132:133]
	s_mov_b32 m0, s63
	ds_read_b128 v[184:187], v153 offset:16384
	ds_read_b128 v[188:191], v153 offset:17408
	ds_read_b128 v[192:195], v153 offset:18432
	ds_read_b128 v[196:199], v153 offset:19456
	ds_read_b128 v[200:203], v153 offset:20480
	ds_read_b128 v[204:207], v153 offset:21504
	ds_read_b128 v[208:211], v153 offset:22528
	ds_read_b128 v[212:215], v153 offset:23552
	global_load_lds_dwordx4 v[216:217], off
	s_add_i32 m0, s63, 0x2000
	s_add_u32 s64, s34, 0x80000
	v_lshl_add_u64 v[218:219], s[34:35], 0, v[128:129]
	s_addc_u32 s65, s35, 0
	s_add_i32 s63, s54, s4
	global_load_lds_dwordx4 v[218:219], off
	v_lshl_add_u64 v[220:221], s[64:65], 0, v[132:133]
	s_mov_b32 m0, s63
	v_lshl_add_u64 v[222:223], s[38:39], 0, v[130:131]
	global_load_lds_dwordx4 v[220:221], off
	v_lshl_add_u64 v[220:221], s[64:65], 0, v[128:129]
	s_add_i32 m0, s63, 0x2000
	s_nop 0
	global_load_lds_dwordx4 v[220:221], off
	v_lshl_add_u64 v[220:221], s[38:39], 0, v[134:135]
	s_mov_b32 m0, s6
	s_nop 0
	global_load_lds_dwordx4 v[220:221], off
	s_mov_b32 m0, s7
	s_nop 0
	global_load_lds_dwordx4 v[222:223], off
	s_waitcnt vmcnt(8)
	s_waitcnt lgkmcnt(0)
	s_barrier
; #define PG8_STAGE(bufoff, gbase, voff) do { _Pragma("unroll") for (int _i = 0; _i < 2; ++_i) \
;         __builtin_amdgcn_global_load_lds((const unsigned*)((const char*)(gbase) + (voff)[_i]), (PG8_LAS unsigned*)(lds + (bufoff) + ldsw + _i * 8192), 16, 0, 0); } while (0)
; #define PG8_LDA(dst, b, h) do { _Pragma("unroll") for (int m = 0; m < 4; ++m) _Pragma("unroll") for (int k = 0; k < 2; ++k) dst[m][k] = *(const PG8_LAS bf16x8*)(lds + PG8_SA(b, h) + aoff + m * 2048 + k * 1024); } while (0)
; #define PG8_WAIT_V(n) asm volatile("s_waitcnt vmcnt(" #n ")" ::: "memory")
; #define PG8_BAR __builtin_amdgcn_s_barrier()
; template <class Epi, class Sched, bool ALIGN_EPI = false, bool SP2 = false>
; __device__ __forceinline__ void gemm_phase(PG8_LAS unsigned char* lds, const Gemm g, const Sched& S, const Epi& E) {
;     ...
;         for (int t = 0; t < nt; t += 2) {
;             const bool last = (t == nt - 2);
;             if constexpr (Epi::HAS_MID) { if (t == E.mid_t) E.mid(acc, cur, wr, wc, fr, fq); }
;             const char* a1 = cA + (size_t)(t + 1) * kstep;
;             const char* a2 = last ? nA : cA + (size_t)(t + 2) * kstep; const char* b2 = last ? nB : cB + (size_t)(t + 2) * kstep;
;             const char* a3 = a2 + kstep; const char* b3 = b2 + kstep;
;             if (last && has_next) S.a_ready(nxt);
;             if constexpr (SP2) {
;             PG8_LDB(B0, 0, 0); PG8_LDB(B1, 0, 1); PG8_SCHED; PG8_LDA(At, 0, 0); PG8_STAGE(PG8_SA(1, 1), a1 + hstepA, voffA);
;             PG8_WAIT_V(8); PG8_WAIT_L(0); PG8_BAR; PG8_MMA(0, 0, At, B0); PG8_MMA(0, 1, At, B1); PG8_BAR; PG8_SCHED;
;             PG8_LDA(At, 0, 1); PG8_STAGE(PG8_SB(0, 0), b2, voffB); PG8_STAGE(PG8_SB(0, 1), b2 + hstepB, voffB); PG8_STAGE(PG8_SA(0, 0), a2, voffA);
;             PG8_WAIT_V(8); PG8_WAIT_L(0); PG8_BAR; PG8_MMA(1, 0, At, B0); PG8_MMA(1, 1, At, B1); PG8_BAR; PG8_SCHED;
;             PG8_LDB(B0, 1, 0); PG8_LDB(B1, 1, 1); PG8_SCHED; PG8_LDA(At, 1, 0); PG8_STAGE(PG8_SA(0, 1), a2 + hstepA, voffA);
;             PG8_WAIT_V(8); PG8_WAIT_L(0); PG8_BAR; PG8_MMA(0, 0, At, B0); PG8_MMA(0, 1, At, B1); PG8_BAR; PG8_SCHED;
;             PG8_LDA(At, 1, 1); PG8_STAGE(PG8_SB(1, 0), b3, voffB); PG8_STAGE(PG8_SB(1, 1), b3 + hstepB, voffB); PG8_STAGE(PG8_SA(1, 0), a3, voffA);
;             PG8_WAIT_V(8); PG8_WAIT_L(0); PG8_BAR; PG8_MMA(1, 0, At, B0); PG8_MMA(1, 1, At, B1); PG8_BAR; PG8_SCHED;
	s_setprio 1
	s_waitcnt lgkmcnt(0)
	v_mfma_f32_16x16x32_bf16 v[60:63], v[144:147], v[184:187], v[60:63]
	v_mfma_f32_16x16x32_bf16 v[52:55], v[160:163], v[184:187], v[52:55]
	v_mfma_f32_16x16x32_bf16 v[44:47], v[144:147], v[192:195], v[44:47]
	v_mfma_f32_16x16x32_bf16 v[36:39], v[160:163], v[192:195], v[36:39]
	v_mfma_f32_16x16x32_bf16 v[28:31], v[144:147], v[200:203], v[28:31]
	v_mfma_f32_16x16x32_bf16 v[20:23], v[160:163], v[200:203], v[20:23]
	v_mfma_f32_16x16x32_bf16 v[12:15], v[144:147], v[208:211], v[12:15]
	v_mfma_f32_16x16x32_bf16 v[4:7], v[160:163], v[208:211], v[4:7]
	v_mfma_f32_16x16x32_bf16 v[60:63], v[156:159], v[188:191], v[60:63]
	v_mfma_f32_16x16x32_bf16 v[52:55], v[164:167], v[188:191], v[52:55]
	v_mfma_f32_16x16x32_bf16 v[44:47], v[156:159], v[196:199], v[44:47]
	v_mfma_f32_16x16x32_bf16 v[36:39], v[164:167], v[196:199], v[36:39]
	v_mfma_f32_16x16x32_bf16 v[28:31], v[156:159], v[204:207], v[28:31]
	v_mfma_f32_16x16x32_bf16 v[20:23], v[164:167], v[204:207], v[20:23]
	v_mfma_f32_16x16x32_bf16 v[12:15], v[156:159], v[212:215], v[12:15]
	v_mfma_f32_16x16x32_bf16 v[4:7], v[164:167], v[212:215], v[4:7]
	s_setprio 0
	s_setprio 1
	v_mfma_f32_16x16x32_bf16 v[56:59], v[168:171], v[184:187], v[56:59]
	v_mfma_f32_16x16x32_bf16 v[48:51], v[176:179], v[184:187], v[48:51]
	v_mfma_f32_16x16x32_bf16 v[40:43], v[168:171], v[192:195], v[40:43]
	v_mfma_f32_16x16x32_bf16 v[32:35], v[176:179], v[192:195], v[32:35]
	v_mfma_f32_16x16x32_bf16 v[24:27], v[168:171], v[200:203], v[24:27]
	v_mfma_f32_16x16x32_bf16 v[16:19], v[176:179], v[200:203], v[16:19]
	v_mfma_f32_16x16x32_bf16 v[8:11], v[168:171], v[208:211], v[8:11]
	v_mfma_f32_16x16x32_bf16 v[0:3], v[176:179], v[208:211], v[0:3]
	v_mfma_f32_16x16x32_bf16 v[56:59], v[172:175], v[188:191], v[56:59]
	v_mfma_f32_16x16x32_bf16 v[48:51], v[180:183], v[188:191], v[48:51]
	v_mfma_f32_16x16x32_bf16 v[40:43], v[172:175], v[196:199], v[40:43]
	v_mfma_f32_16x16x32_bf16 v[32:35], v[180:183], v[196:199], v[32:35]
	v_mfma_f32_16x16x32_bf16 v[24:27], v[172:175], v[204:207], v[24:27]
	v_mfma_f32_16x16x32_bf16 v[16:19], v[180:183], v[204:207], v[16:19]
	v_mfma_f32_16x16x32_bf16 v[8:11], v[172:175], v[212:215], v[8:11]
	v_mfma_f32_16x16x32_bf16 v[0:3], v[180:183], v[212:215], v[0:3]
	s_setprio 0
	s_barrier
	s_add_i32 s63, 0, 0x18000
	v_add_u32_e32 v155, s63, v150
	s_add_i32 s64, 0, 0x1c000
	ds_read_b128 v[144:147], v155
	ds_read_b128 v[156:159], v155 offset:1024
	ds_read_b128 v[160:163], v155 offset:2048
	ds_read_b128 v[164:167], v155 offset:3072
	v_add_u32_e32 v155, s64, v150
	ds_read_b128 v[168:171], v155
	ds_read_b128 v[172:175], v155 offset:1024
	ds_read_b128 v[176:179], v155 offset:2048
	ds_read_b128 v[180:183], v155 offset:3072
	s_add_u32 s38, s38, 0x80000
	s_addc_u32 s39, s39, 0
	s_mov_b32 m0, s41
	v_lshl_add_u64 v[224:225], s[38:39], 0, v[134:135]
	global_load_lds_dwordx4 v[224:225], off
	v_lshl_add_u64 v[224:225], s[38:39], 0, v[130:131]
	s_mov_b32 m0, s42
	s_nop 0
	global_load_lds_dwordx4 v[224:225], off
	s_waitcnt vmcnt(8)
	s_waitcnt lgkmcnt(0)
	s_barrier
	s_setprio 1
	s_waitcnt lgkmcnt(0)
	s_setprio 0
	s_setprio 1
	s_setprio 0
	s_barrier
	s_add_i32 s38, s63, s4
	v_lshl_add_u64 v[216:217], v[216:217], 0, s[16:17]
	s_mov_b32 m0, s38
	ds_read_b128 v[184:187], v153 offset:49152
	ds_read_b128 v[188:191], v153 offset:50176
	ds_read_b128 v[192:195], v153 offset:51200
	ds_read_b128 v[196:199], v153 offset:52224
	ds_read_b128 v[200:203], v153 offset:53248
	ds_read_b128 v[204:207], v153 offset:54272
	ds_read_b128 v[208:211], v153 offset:55296
	ds_read_b128 v[212:215], v153 offset:56320
	global_load_lds_dwordx4 v[216:217], off
	s_add_i32 m0, s38, 0x2000
	s_add_u32 s34, s34, 0x80080
	v_lshl_add_u64 v[216:217], v[218:219], 0, s[16:17]
	s_addc_u32 s35, s35, 0
	s_add_i32 s38, s64, s4
	global_load_lds_dwordx4 v[216:217], off
	v_lshl_add_u64 v[216:217], s[34:35], 0, v[132:133]
	s_mov_b32 m0, s38
	s_nop 0
	global_load_lds_dwordx4 v[216:217], off
	v_lshl_add_u64 v[216:217], s[34:35], 0, v[128:129]
	s_add_i32 m0, s38, 0x2000
	s_nop 0
	global_load_lds_dwordx4 v[216:217], off
	v_lshl_add_u64 v[216:217], v[220:221], 0, s[16:17]
	s_mov_b32 m0, s46
	s_nop 0
	global_load_lds_dwordx4 v[216:217], off
	v_lshl_add_u64 v[216:217], v[222:223], 0, s[16:17]
	s_mov_b32 m0, s47
	s_nop 0
	global_load_lds_dwordx4 v[216:217], off
	s_waitcnt vmcnt(8)
	s_waitcnt lgkmcnt(0)
	s_barrier
	s_setprio 1
	s_waitcnt lgkmcnt(0)
	v_mfma_f32_16x16x32_bf16 v[60:63], v[144:147], v[184:187], v[60:63]
	v_mfma_f32_16x16x32_bf16 v[52:55], v[160:163], v[184:187], v[52:55]
	v_mfma_f32_16x16x32_bf16 v[44:47], v[144:147], v[192:195], v[44:47]
	v_mfma_f32_16x16x32_bf16 v[36:39], v[160:163], v[192:195], v[36:39]
	v_mfma_f32_16x16x32_bf16 v[28:31], v[144:147], v[200:203], v[28:31]
	v_mfma_f32_16x16x32_bf16 v[20:23], v[160:163], v[200:203], v[20:23]
	v_mfma_f32_16x16x32_bf16 v[12:15], v[144:147], v[208:211], v[12:15]
	v_mfma_f32_16x16x32_bf16 v[4:7], v[160:163], v[208:211], v[4:7]
	v_mfma_f32_16x16x32_bf16 v[60:63], v[156:159], v[188:191], v[60:63]
	v_mfma_f32_16x16x32_bf16 v[52:55], v[164:167], v[188:191], v[52:55]
	v_mfma_f32_16x16x32_bf16 v[44:47], v[156:159], v[196:199], v[44:47]
	v_mfma_f32_16x16x32_bf16 v[36:39], v[164:167], v[196:199], v[36:39]
	v_mfma_f32_16x16x32_bf16 v[28:31], v[156:159], v[204:207], v[28:31]
	v_mfma_f32_16x16x32_bf16 v[20:23], v[164:167], v[204:207], v[20:23]
	v_mfma_f32_16x16x32_bf16 v[12:15], v[156:159], v[212:215], v[12:15]
	v_mfma_f32_16x16x32_bf16 v[4:7], v[164:167], v[212:215], v[4:7]
	s_setprio 0
	s_setprio 1
	v_mfma_f32_16x16x32_bf16 v[56:59], v[168:171], v[184:187], v[56:59]
	v_mfma_f32_16x16x32_bf16 v[48:51], v[176:179], v[184:187], v[48:51]
	v_mfma_f32_16x16x32_bf16 v[40:43], v[168:171], v[192:195], v[40:43]
	v_mfma_f32_16x16x32_bf16 v[32:35], v[176:179], v[192:195], v[32:35]
	v_mfma_f32_16x16x32_bf16 v[24:27], v[168:171], v[200:203], v[24:27]
	v_mfma_f32_16x16x32_bf16 v[16:19], v[176:179], v[200:203], v[16:19]
	v_mfma_f32_16x16x32_bf16 v[8:11], v[168:171], v[208:211], v[8:11]
	v_mfma_f32_16x16x32_bf16 v[0:3], v[176:179], v[208:211], v[0:3]
	v_mfma_f32_16x16x32_bf16 v[56:59], v[172:175], v[188:191], v[56:59]
	v_mfma_f32_16x16x32_bf16 v[48:51], v[180:183], v[188:191], v[48:51]
	v_mfma_f32_16x16x32_bf16 v[40:43], v[172:175], v[196:199], v[40:43]
	v_mfma_f32_16x16x32_bf16 v[32:35], v[180:183], v[196:199], v[32:35]
	v_mfma_f32_16x16x32_bf16 v[24:27], v[172:175], v[204:207], v[24:27]
	v_mfma_f32_16x16x32_bf16 v[16:19], v[180:183], v[204:207], v[16:19]
	v_mfma_f32_16x16x32_bf16 v[8:11], v[172:175], v[212:215], v[8:11]
	v_mfma_f32_16x16x32_bf16 v[0:3], v[180:183], v[212:215], v[0:3]
	s_setprio 0
	s_barrier
	s_add_i32 s62, s62, 2
	s_add_u32 s30, s30, 0x100
	s_addc_u32 s31, s31, 0
	s_add_u32 s60, s60, 0x100
	s_addc_u32 s61, s61, 0
	s_cmp_gt_u32 s62, 29
	s_cbranch_scc0 .Lp7h1_loop
	s_branch .Lp7_after_loop
; __device__ __forceinline__ float sigmoidf_(float x) { return __builtin_amdgcn_rcpf(1.0f + __expf(-x)); }
; __device__ __forceinline__ u32x4 pack8(const f32x4& a, const f32x4& b) { u32x4 w; w.x = cvt_pk_bf16(a[0], a[1]); w.y = cvt_pk_bf16(a[2], a[3]); w.z = cvt_pk_bf16(b[0], b[1]); w.w = cvt_pk_bf16(b[2], b[3]); return w; }
;     __device__ __forceinline__ void operator()(const f32x4 (&acc)[2][2][4][2], const Unit& u, int wr, int wc, int fr, int fq) const {
;     ...
;             for (int m = 0; m < 4; ++m) { const size_t row = (size_t)u.pm * BM + ai * HALF + wr * 64 + m * 16 + fr;
;                 const float rs = tab[ai * HALF + wr * 64 + m * 16 + fr];
;                 f32x4 h[2];
; #pragma unroll
;                 for (int n = 0; n < 2; ++n) { const f32x4 g = acc[ai][0][m][n] * rs, up = acc[ai][1][m][n] * rs;
; #pragma unroll
;                     for (int j = 0; j < 4; ++j) h[n][j] = g[j] * sigmoidf_(g[j]) * up[j]; }
;                 *(u32x4*)(H + row * 5632 + u.pn * HALF + wc * 32 + fq * 8) = pack8(h[0], h[1]); }
.Lp7_h1_epi:
	s_lshl_b32 s20, s58, 7
	s_ashr_i32 s21, s20, 31
	v_ashrrev_i32_e32 v145, 31, v144
	v_mov_b64_e32 v[112:113], s[44:45]
	v_mad_u64_u32 v[112:113], s[30:31], v146, s56, v[112:113]
	v_mad_i32_i24 v113, v147, s56, v113
	v_lshl_add_u64 v[112:113], s[20:21], 1, v[112:113]
	v_lshl_add_u64 v[112:113], v[112:113], 0, s[12:13]
	v_lshl_add_u64 v[112:113], v[144:145], 1, v[112:113]
	s_mov_b32 s20, 0x160000
	s_branch .Lp7_blk4
.Lp7_h0_skip:
	s_mov_b64 s[20:21], -1
	s_andn2_b64 vcc, exec, s[36:37]
	s_branch .Lp7_epi_tail
